# GEMM phases: one static s_setprio 1 for the wave half that enters the ping-pong a phase late, no per-segment priority toggling
# speedup vs baseline: 1.0092x; 1.0068x over previous
; #define PG8_STAGE(bufoff, gbase, voff) do { _Pragma("unroll") for (int _i = 0; _i < 2; ++_i) \
;         __builtin_amdgcn_global_load_lds((const unsigned*)((const char*)(gbase) + (voff)[_i]), (LAS unsigned*)(lds + (bufoff) + ldsw + _i * 8192), 16, 0, 0); } while (0)
; #define PG8_BAR __builtin_amdgcn_s_barrier()
; template <class Epi>
; __device__ __forceinline__ void gemm_phase(LAS unsigned char* lds, const Gemm g, const StaticOrder& S, const Epi& E) {
;     const int tid = threadIdx.x, wid = __builtin_amdgcn_readfirstlane(tid >> 6), lane = tid & 63, wr = wid >> 2, wc = wid & 3, fr = lane & 15, fq = lane >> 4;
;     const int K = g.K, nt = K / BK;
;     unsigned voffA[2], voffB[2];
; #pragma unroll
;     for (int i = 0; i < 2; ++i) { int R, C; stage_rc(tid * 16 + i * 8192, R, C); const int Rb = Epi::PERM ? ((R & ~31) + perm32(R & 31)) : R; voffA[i] = (unsigned)(R * K + C) * 2u; voffB[i] = (unsigned)(Rb * K + C) * 2u; }
;     const size_t kstep = (size_t)(BK * 2);
;     const size_t hstep = (size_t)HALF * K * 2;
;     const size_t tstep = 2 * hstep;
;     const unsigned ldsw = (unsigned)wid * 1024u;
;     const int aoff = lds_byte(wr * 64 + fr, fq * 8), boff = lds_byte(wc * 32 + fr, fq * 8);
;     ...
;     Unit cur, nxt; int ui = 0;
;     if (!S.next(0, cur)) return;
;     f32x4 acc[2][2][4][2];
; #pragma unroll
;     for (int a = 0; a < 2; ++a)
; #pragma unroll
;         for (int b = 0; b < 2; ++b)
; #pragma unroll
;             for (int m = 0; m < 4; ++m)
; #pragma unroll
;                 for (int n = 0; n < 2; ++n) acc[a][b][m][n] = (f32x4){0.f, 0.f, 0.f, 0.f};
;     h16x8 At[4][2], B0[2][2], B1[2][2];
;     const char* cA = (const char*)g.A + (size_t)cur.pm * tstep; const char* cB = (const char*)g.Bt + (size_t)cur.pn * tstep;
;     PG8_STAGE(PG8_SB(0, 0), cB, voffB); PG8_STAGE(PG8_SA(0, 0), cA, voffA); PG8_STAGE(PG8_SB(0, 1), cB + hstep, voffB); PG8_STAGE(PG8_SA(0, 1), cA + hstep, voffA);
;     if (wr == 1) PG8_BAR;
.LBB0_187:
	s_andn2_b64 vcc, exec, s[0:1]
	s_cbranch_vccnz .LBB0_223
	v_lshrrev_b32_e32 v2, 1, v130
	v_lshrrev_b32_e32 v3, 5, v130
	v_and_b32_e32 v2, 24, v2
	v_and_b32_e32 v3, 4, v3
	v_bfe_u32 v4, v130, 2, 2
	v_lshlrev_b32_e32 v0, 4, v130
	v_and_b32_e32 v1, 32, v130
	v_bfe_u32 v10, v130, 2, 4
	v_or3_b32 v2, v3, v4, v2
	v_lshrrev_b32_e32 v3, 3, v130
	s_movk_i32 s0, 0x70
	v_bitop3_b32 v8, v0, v1, 48 bitop3:0x6c
	v_and_b32_e32 v9, 64, v130
	v_and_or_b32 v4, v3, s0, v10
	s_movk_i32 s0, 0x60
	v_add_u32_e32 v11, 0x2000, v0
	v_or_b32_e32 v1, v8, v9
	v_and_or_b32 v3, v3, s0, v2
	v_lshrrev_b32_e32 v0, 7, v11
	s_movk_i32 s0, 0xf0
	v_lshl_or_b32 v132, v3, 11, v1
	v_and_or_b32 v3, v0, s0, v10
	s_movk_i32 s0, 0xe0
	v_and_or_b32 v0, v0, s0, v2
	s_lshr_b32 s0, s10, 6
	s_ashr_i32 s79, s78, 31
	s_ashr_i32 s77, s76, 31
	v_writelane_b32 v254, s10, 5
	s_lshr_b32 s4, s10, 8
	s_lshl_b32 s87, s0, 10
	s_lshl_b64 s[8:9], s[78:79], 19
	s_lshl_b64 s[10:11], s[76:77], 19
	s_add_u32 s82, s70, s10
	s_addc_u32 s83, s71, s11
	s_add_i32 s77, s87, 0
	s_add_i32 m0, s77, 0x10000
	v_lshl_or_b32 v136, v0, 11, v1
	global_load_lds_dwordx4 v132, s[82:83]
	s_add_i32 m0, s77, 0x12000
	s_add_u32 s80, s68, s8
	v_lshl_or_b32 v128, v4, 11, v1
	global_load_lds_dwordx4 v136, s[82:83]
	s_addc_u32 s81, s69, s9
	s_mov_b32 m0, s77
	s_add_i32 s88, s77, 0x2000
	v_lshl_or_b32 v134, v3, 11, v1
	global_load_lds_dwordx4 v128, s[80:81]
	s_mov_b32 m0, s88
	s_add_u32 s8, s82, 0x40000
	global_load_lds_dwordx4 v134, s[80:81]
	s_addc_u32 s9, s83, 0
	s_add_i32 m0, s77, 0x14000
	v_mov_b32_e32 v139, 0
	global_load_lds_dwordx4 v132, s[8:9]
	s_add_i32 m0, s77, 0x16000
	v_mov_b32_e32 v133, v139
	global_load_lds_dwordx4 v136, s[8:9]
	s_add_u32 s8, s80, 0x40000
	s_addc_u32 s9, s81, 0
	s_add_i32 s89, s77, 0x4000
	s_mov_b32 m0, s89
	s_add_i32 s90, s77, 0x6000
	global_load_lds_dwordx4 v128, s[8:9]
	s_mov_b32 m0, s90
	v_mov_b32_e32 v137, v139
	global_load_lds_dwordx4 v134, s[8:9]
	v_mov_b32_e32 v129, v139
	v_mov_b32_e32 v135, v139
	s_mov_b32 s91, 0
	v_lshl_add_u64 v[6:7], s[82:83], 0, v[132:133]
	v_lshl_add_u64 v[4:5], s[82:83], 0, v[136:137]
	v_lshl_add_u64 v[2:3], s[80:81], 0, v[128:129]
	s_cmp_lg_u32 s4, 1
	v_lshl_add_u64 v[0:1], s[80:81], 0, v[134:135]
	s_cbranch_scc1 .LBB0_190
	s_barrier
	s_setprio 1

; #define PG8_STAGE(bufoff, gbase, voff) do { _Pragma("unroll") for (int _i = 0; _i < 2; ++_i) \
;         __builtin_amdgcn_global_load_lds((const unsigned*)((const char*)(gbase) + (voff)[_i]), (LAS unsigned*)(lds + (bufoff) + ldsw + _i * 8192), 16, 0, 0); } while (0)
; #define PG8_LDA(dst, b, h) do { _Pragma("unroll") for (int m = 0; m < 4; ++m) _Pragma("unroll") for (int k = 0; k < 2; ++k) dst[m][k] = *(const LAS h16x8*)(lds + PG8_SA(b, h) + aoff + m * 2048 + k * 1024); } while (0)
; #define PG8_LDB(dst, b, h) do { _Pragma("unroll") for (int n = 0; n < 2; ++n) _Pragma("unroll") for (int k = 0; k < 2; ++k) dst[n][k] = *(const LAS h16x8*)(lds + PG8_SB(b, h) + boff + n * 2048 + k * 1024); } while (0)
; #define PG8_MMA(ai, bj, At, Bt) do { __builtin_amdgcn_s_setprio(1); _Pragma("unroll") for (int m = 0; m < 4; ++m) _Pragma("unroll") for (int n = 0; n < 2; ++n) _Pragma("unroll") for (int k = 0; k < 2; ++k) \
;         acc[ai][bj][m][n] = __builtin_amdgcn_mfma_f32_16x16x32_f16(Bt[n][k], At[m][k], acc[ai][bj][m][n], 0, 0, 0); __builtin_amdgcn_s_setprio(0); } while (0)
; #define PG8_WAIT_L(n) asm volatile("s_waitcnt lgkmcnt(" #n ")" ::: "memory")
; #define PG8_BAR __builtin_amdgcn_s_barrier()
; #define PG8_SCHED __builtin_amdgcn_sched_barrier(0)
; template <class Epi>
; __device__ __forceinline__ void gemm_phase(LAS unsigned char* lds, const Gemm g, const StaticOrder& S, const Epi& E) {
;     ...
;             PG8_LDB(B0, 0, 0); PG8_SCHED; PG8_LDA(At, 0, 0); PG8_STAGE(PG8_SA(1, 1), a1 + hstep, voffA);
;             PG8_WAIT_L(8); PG8_BAR; PG8_WAIT_L(0); PG8_MMA(0, 0, At, B0); PG8_BAR; PG8_SCHED;
;             PG8_LDB(B1, 0, 1); PG8_STAGE(PG8_SB(0, 0), b2, voffB);
;             PG8_BAR; PG8_WAIT_L(0); PG8_MMA(0, 1, At, B1); PG8_BAR;
;             PG8_LDA(At, 0, 1); PG8_STAGE(PG8_SA(0, 0), a2, voffA);
;             PG8_BAR; PG8_WAIT_L(0); PG8_MMA(1, 0, At, B0); PG8_BAR; PG8_SCHED;
;             PG8_STAGE(PG8_SB(0, 1), b2 + hstep, voffB);
.LBB0_195:
	ds_read_b128 v[148:151], v159
	ds_read_b128 v[164:167], v159 offset:1024
	ds_read_b128 v[168:171], v159 offset:2048
	ds_read_b128 v[172:175], v159 offset:3072
	s_add_u32 s34, s80, 0xfffc0080
	s_addc_u32 s35, s81, -1
	s_cmp_eq_u32 s15, 12
	s_cselect_b32 s85, s49, s35
	s_cselect_b32 s84, s79, s34
	s_cselect_b32 s83, s47, s14
	s_cselect_b32 s82, vcc_lo, vcc_hi
	s_waitcnt lgkmcnt(0)
	v_lshl_add_u64 v[152:153], s[80:81], 0, v[140:141]
	s_add_i32 m0, s77, 0xc000
	ds_read_b128 v[176:179], v160
	ds_read_b128 v[180:183], v160 offset:1024
	ds_read_b128 v[184:187], v160 offset:2048
	ds_read_b128 v[188:191], v160 offset:3072
	ds_read_b128 v[192:195], v160 offset:4096
	ds_read_b128 v[196:199], v160 offset:5120
	ds_read_b128 v[200:203], v160 offset:6144
	ds_read_b128 v[204:207], v160 offset:7168
	global_load_lds_dwordx4 v[152:153], off
	v_lshl_add_u64 v[152:153], s[80:81], 0, v[142:143]
	s_add_i32 m0, s77, 0xe000
	s_nop 0
	global_load_lds_dwordx4 v[152:153], off
	s_waitcnt lgkmcnt(8)
	s_barrier
	s_waitcnt lgkmcnt(0)
	s_waitcnt lgkmcnt(0)
	v_mfma_f32_16x16x32_f16 v[124:127], v[148:151], v[176:179], v[124:127]
	v_mfma_f32_16x16x32_f16 v[120:123], v[168:171], v[176:179], v[120:123]
	v_mfma_f32_16x16x32_f16 v[108:111], v[148:151], v[184:187], v[108:111]
	v_mfma_f32_16x16x32_f16 v[104:107], v[168:171], v[184:187], v[104:107]
	v_mfma_f32_16x16x32_f16 v[92:95], v[148:151], v[192:195], v[92:95]
	v_mfma_f32_16x16x32_f16 v[88:91], v[168:171], v[192:195], v[88:91]
	v_mfma_f32_16x16x32_f16 v[76:79], v[148:151], v[200:203], v[76:79]
	v_mfma_f32_16x16x32_f16 v[72:75], v[168:171], v[200:203], v[72:75]
	v_mfma_f32_16x16x32_f16 v[124:127], v[164:167], v[180:183], v[124:127]
	v_mfma_f32_16x16x32_f16 v[120:123], v[172:175], v[180:183], v[120:123]
	v_mfma_f32_16x16x32_f16 v[108:111], v[164:167], v[188:191], v[108:111]
	v_mfma_f32_16x16x32_f16 v[104:107], v[172:175], v[188:191], v[104:107]
	v_mfma_f32_16x16x32_f16 v[92:95], v[164:167], v[196:199], v[92:95]
	v_mfma_f32_16x16x32_f16 v[88:91], v[172:175], v[196:199], v[88:91]
	v_mfma_f32_16x16x32_f16 v[76:79], v[164:167], v[204:207], v[76:79]
	v_mfma_f32_16x16x32_f16 v[72:75], v[172:175], v[204:207], v[72:75]
	s_barrier
	s_add_i32 s34, s97, s87
	v_lshl_add_u64 v[152:153], s[82:83], 0, v[132:133]
	s_mov_b32 m0, s34
	ds_read_b128 v[208:211], v161
	ds_read_b128 v[212:215], v161 offset:1024
	ds_read_b128 v[216:219], v161 offset:2048
	ds_read_b128 v[220:223], v161 offset:3072
	global_load_lds_dwordx4 v[152:153], off
	v_lshl_add_u64 v[224:225], s[82:83], 0, v[136:137]
	s_add_i32 m0, s34, 0x2000
	s_nop 0
	global_load_lds_dwordx4 v[224:225], off
	s_barrier
	s_waitcnt lgkmcnt(0)
	s_waitcnt lgkmcnt(0)
	v_mfma_f32_16x16x32_f16 v[116:119], v[208:211], v[176:179], v[116:119]
	v_mfma_f32_16x16x32_f16 v[112:115], v[216:219], v[176:179], v[112:115]
	v_mfma_f32_16x16x32_f16 v[100:103], v[208:211], v[184:187], v[100:103]
	v_mfma_f32_16x16x32_f16 v[96:99], v[216:219], v[184:187], v[96:99]
	v_mfma_f32_16x16x32_f16 v[84:87], v[208:211], v[192:195], v[84:87]
	v_mfma_f32_16x16x32_f16 v[80:83], v[216:219], v[192:195], v[80:83]
	v_mfma_f32_16x16x32_f16 v[68:71], v[208:211], v[200:203], v[68:71]
	v_mfma_f32_16x16x32_f16 v[64:67], v[216:219], v[200:203], v[64:67]
	v_mfma_f32_16x16x32_f16 v[116:119], v[212:215], v[180:183], v[116:119]
	v_mfma_f32_16x16x32_f16 v[112:115], v[220:223], v[180:183], v[112:115]
	v_mfma_f32_16x16x32_f16 v[100:103], v[212:215], v[188:191], v[100:103]
	v_mfma_f32_16x16x32_f16 v[96:99], v[220:223], v[188:191], v[96:99]
	v_mfma_f32_16x16x32_f16 v[84:87], v[212:215], v[196:199], v[84:87]
	v_mfma_f32_16x16x32_f16 v[80:83], v[220:223], v[196:199], v[80:83]
	v_mfma_f32_16x16x32_f16 v[68:71], v[212:215], v[204:207], v[68:71]
	v_mfma_f32_16x16x32_f16 v[64:67], v[220:223], v[204:207], v[64:67]
	s_mov_b32 m0, s77
	v_lshl_add_u64 v[226:227], s[84:85], 0, v[128:129]
	s_barrier
	ds_read_b128 v[176:179], v160 offset:16384
	ds_read_b128 v[180:183], v160 offset:17408
	ds_read_b128 v[184:187], v160 offset:18432
	ds_read_b128 v[188:191], v160 offset:19456
	ds_read_b128 v[192:195], v160 offset:20480
	ds_read_b128 v[196:199], v160 offset:21504
	ds_read_b128 v[200:203], v160 offset:22528
	ds_read_b128 v[204:207], v160 offset:23552
	global_load_lds_dwordx4 v[226:227], off
	v_lshl_add_u64 v[228:229], s[84:85], 0, v[134:135]
	s_mov_b32 m0, s88
	s_nop 0
	global_load_lds_dwordx4 v[228:229], off
	s_barrier
	s_waitcnt lgkmcnt(0)
	s_waitcnt lgkmcnt(0)
	v_mfma_f32_16x16x32_f16 v[60:63], v[148:151], v[176:179], v[60:63]
	v_mfma_f32_16x16x32_f16 v[56:59], v[168:171], v[176:179], v[56:59]
	v_mfma_f32_16x16x32_f16 v[44:47], v[148:151], v[184:187], v[44:47]
	v_mfma_f32_16x16x32_f16 v[40:43], v[168:171], v[184:187], v[40:43]
	v_mfma_f32_16x16x32_f16 v[28:31], v[148:151], v[192:195], v[28:31]
	v_mfma_f32_16x16x32_f16 v[24:27], v[168:171], v[192:195], v[24:27]
	v_mfma_f32_16x16x32_f16 v[12:15], v[148:151], v[200:203], v[12:15]
	v_mfma_f32_16x16x32_f16 v[8:11], v[168:171], v[200:203], v[8:11]
	v_mfma_f32_16x16x32_f16 v[60:63], v[164:167], v[180:183], v[60:63]
	v_mfma_f32_16x16x32_f16 v[56:59], v[172:175], v[180:183], v[56:59]
	v_mfma_f32_16x16x32_f16 v[44:47], v[164:167], v[188:191], v[44:47]
	v_mfma_f32_16x16x32_f16 v[40:43], v[172:175], v[188:191], v[40:43]
	v_mfma_f32_16x16x32_f16 v[28:31], v[164:167], v[196:199], v[28:31]
	v_mfma_f32_16x16x32_f16 v[24:27], v[172:175], v[196:199], v[24:27]
	v_mfma_f32_16x16x32_f16 v[12:15], v[164:167], v[204:207], v[12:15]
	v_mfma_f32_16x16x32_f16 v[8:11], v[172:175], v[204:207], v[8:11]
	s_barrier
; #define PG8_STAGE(bufoff, gbase, voff) do { _Pragma("unroll") for (int _i = 0; _i < 2; ++_i) \
;         __builtin_amdgcn_global_load_lds((const unsigned*)((const char*)(gbase) + (voff)[_i]), (LAS unsigned*)(lds + (bufoff) + ldsw + _i * 8192), 16, 0, 0); } while (0)
; #define PG8_LDA(dst, b, h) do { _Pragma("unroll") for (int m = 0; m < 4; ++m) _Pragma("unroll") for (int k = 0; k < 2; ++k) dst[m][k] = *(const LAS h16x8*)(lds + PG8_SA(b, h) + aoff + m * 2048 + k * 1024); } while (0)
; #define PG8_LDB(dst, b, h) do { _Pragma("unroll") for (int n = 0; n < 2; ++n) _Pragma("unroll") for (int k = 0; k < 2; ++k) dst[n][k] = *(const LAS h16x8*)(lds + PG8_SB(b, h) + boff + n * 2048 + k * 1024); } while (0)
; #define PG8_MMA(ai, bj, At, Bt) do { __builtin_amdgcn_s_setprio(1); _Pragma("unroll") for (int m = 0; m < 4; ++m) _Pragma("unroll") for (int n = 0; n < 2; ++n) _Pragma("unroll") for (int k = 0; k < 2; ++k) \
;         acc[ai][bj][m][n] = __builtin_amdgcn_mfma_f32_16x16x32_f16(Bt[n][k], At[m][k], acc[ai][bj][m][n], 0, 0, 0); __builtin_amdgcn_s_setprio(0); } while (0)
; #define PG8_WAIT_V(n) asm volatile("s_waitcnt vmcnt(" #n ")" ::: "memory")
; #define PG8_WAIT_L(n) asm volatile("s_waitcnt lgkmcnt(" #n ")" ::: "memory")
; #define PG8_BAR __builtin_amdgcn_s_barrier()
; #define PG8_SCHED __builtin_amdgcn_sched_barrier(0)
; template <class Epi>
; __device__ __forceinline__ void gemm_phase(LAS unsigned char* lds, const Gemm g, const StaticOrder& S, const Epi& E) {
;     ...
;             PG8_STAGE(PG8_SB(0, 1), b2 + hstep, voffB);
;             PG8_WAIT_V(6); PG8_BAR; PG8_MMA(1, 1, At, B1); PG8_BAR;
;             PG8_LDB(B0, 1, 0); PG8_SCHED; PG8_LDA(At, 1, 0); PG8_STAGE(PG8_SA(0, 1), a2 + hstep, voffA);
;             PG8_WAIT_L(8); PG8_BAR; PG8_WAIT_L(0); PG8_MMA(0, 0, At, B0); PG8_BAR; PG8_SCHED;
;             PG8_LDB(B1, 1, 1); PG8_STAGE(PG8_SB(1, 0), b3, voffB);
;             PG8_BAR; PG8_WAIT_L(0); PG8_MMA(0, 1, At, B1); PG8_BAR;
;             PG8_LDA(At, 1, 1); PG8_STAGE(PG8_SA(1, 0), a3, voffA);
;             PG8_BAR; PG8_WAIT_L(0); PG8_MMA(1, 0, At, B0); PG8_BAR; PG8_SCHED;
	s_add_u32 s34, s82, 0x40000
	s_addc_u32 s35, s83, 0
	s_add_i32 s86, s33, s87
	v_lshl_add_u64 v[148:149], s[34:35], 0, v[132:133]
	s_mov_b32 m0, s86
	s_nop 0
	global_load_lds_dwordx4 v[148:149], off
	v_lshl_add_u64 v[148:149], s[34:35], 0, v[136:137]
	s_add_i32 m0, s86, 0x2000
	s_nop 0
	global_load_lds_dwordx4 v[148:149], off
	s_waitcnt vmcnt(6)
	s_barrier
	v_mfma_f32_16x16x32_f16 v[52:55], v[208:211], v[176:179], v[52:55]
	v_mfma_f32_16x16x32_f16 v[48:51], v[216:219], v[176:179], v[48:51]
	v_mfma_f32_16x16x32_f16 v[36:39], v[208:211], v[184:187], v[36:39]
	v_mfma_f32_16x16x32_f16 v[32:35], v[216:219], v[184:187], v[32:35]
	v_mfma_f32_16x16x32_f16 v[20:23], v[208:211], v[192:195], v[20:23]
	v_mfma_f32_16x16x32_f16 v[16:19], v[216:219], v[192:195], v[16:19]
	v_mfma_f32_16x16x32_f16 v[4:7], v[208:211], v[200:203], v[4:7]
	v_mfma_f32_16x16x32_f16 v[0:3], v[216:219], v[200:203], v[0:3]
	v_mfma_f32_16x16x32_f16 v[52:55], v[212:215], v[180:183], v[52:55]
	v_mfma_f32_16x16x32_f16 v[48:51], v[220:223], v[180:183], v[48:51]
	v_mfma_f32_16x16x32_f16 v[36:39], v[212:215], v[188:191], v[36:39]
	v_mfma_f32_16x16x32_f16 v[32:35], v[220:223], v[188:191], v[32:35]
	v_mfma_f32_16x16x32_f16 v[20:23], v[212:215], v[196:199], v[20:23]
	v_mfma_f32_16x16x32_f16 v[16:19], v[220:223], v[196:199], v[16:19]
	v_mfma_f32_16x16x32_f16 v[4:7], v[212:215], v[204:207], v[4:7]
	v_mfma_f32_16x16x32_f16 v[0:3], v[220:223], v[204:207], v[0:3]
	s_add_i32 s86, 0, 0x18000
	v_add_u32_e32 v138, s86, v155
	s_barrier
	ds_read_b128 v[148:151], v138
	ds_read_b128 v[164:167], v138 offset:1024
	ds_read_b128 v[168:171], v138 offset:2048
	ds_read_b128 v[172:175], v138 offset:3072
	s_add_u32 s34, s84, 0x40000
	s_addc_u32 s35, s85, 0
	s_mov_b32 m0, s89
	v_lshl_add_u64 v[208:209], s[34:35], 0, v[128:129]
	ds_read_b128 v[176:179], v160 offset:32768
	ds_read_b128 v[180:183], v160 offset:33792
	ds_read_b128 v[184:187], v160 offset:34816
	ds_read_b128 v[188:191], v160 offset:35840
	ds_read_b128 v[192:195], v160 offset:36864
	ds_read_b128 v[196:199], v160 offset:37888
	ds_read_b128 v[200:203], v160 offset:38912
	ds_read_b128 v[204:207], v160 offset:39936
	global_load_lds_dwordx4 v[208:209], off
	v_lshl_add_u64 v[208:209], s[34:35], 0, v[134:135]
	s_mov_b32 m0, s90
	s_nop 0
	global_load_lds_dwordx4 v[208:209], off
	s_waitcnt lgkmcnt(8)
	s_barrier
	s_waitcnt lgkmcnt(0)
	s_waitcnt lgkmcnt(0)
	v_mfma_f32_16x16x32_f16 v[124:127], v[148:151], v[176:179], v[124:127]
	v_mfma_f32_16x16x32_f16 v[120:123], v[168:171], v[176:179], v[120:123]
	v_mfma_f32_16x16x32_f16 v[108:111], v[148:151], v[184:187], v[108:111]
	v_mfma_f32_16x16x32_f16 v[104:107], v[168:171], v[184:187], v[104:107]
	v_mfma_f32_16x16x32_f16 v[92:95], v[148:151], v[192:195], v[92:95]
	v_mfma_f32_16x16x32_f16 v[88:91], v[168:171], v[192:195], v[88:91]
	v_mfma_f32_16x16x32_f16 v[76:79], v[148:151], v[200:203], v[76:79]
	v_mfma_f32_16x16x32_f16 v[72:75], v[168:171], v[200:203], v[72:75]
	v_mfma_f32_16x16x32_f16 v[124:127], v[164:167], v[180:183], v[124:127]
	v_mfma_f32_16x16x32_f16 v[120:123], v[172:175], v[180:183], v[120:123]
	v_mfma_f32_16x16x32_f16 v[108:111], v[164:167], v[188:191], v[108:111]
	v_mfma_f32_16x16x32_f16 v[104:107], v[172:175], v[188:191], v[104:107]
	v_mfma_f32_16x16x32_f16 v[92:95], v[164:167], v[196:199], v[92:95]
	v_mfma_f32_16x16x32_f16 v[88:91], v[172:175], v[196:199], v[88:91]
	v_mfma_f32_16x16x32_f16 v[76:79], v[164:167], v[204:207], v[76:79]
	v_mfma_f32_16x16x32_f16 v[72:75], v[172:175], v[204:207], v[72:75]
	s_barrier
	s_add_i32 s84, 0, 0x1c000
	s_add_i32 s34, s86, s87
	v_add_u32_e32 v138, s84, v155
	v_lshl_add_u64 v[152:153], v[152:153], 0, s[28:29]
	s_mov_b32 m0, s34
	ds_read_b128 v[208:211], v138
	ds_read_b128 v[212:215], v138 offset:1024
	ds_read_b128 v[216:219], v138 offset:2048
	ds_read_b128 v[220:223], v138 offset:3072
	global_load_lds_dwordx4 v[152:153], off
	v_lshl_add_u64 v[152:153], v[224:225], 0, s[28:29]
	s_add_i32 m0, s34, 0x2000
	s_nop 0
	global_load_lds_dwordx4 v[152:153], off
	s_barrier
	s_waitcnt lgkmcnt(0)
	s_waitcnt lgkmcnt(0)
	v_mfma_f32_16x16x32_f16 v[116:119], v[208:211], v[176:179], v[116:119]
	v_mfma_f32_16x16x32_f16 v[112:115], v[216:219], v[176:179], v[112:115]
	v_mfma_f32_16x16x32_f16 v[100:103], v[208:211], v[184:187], v[100:103]
	v_mfma_f32_16x16x32_f16 v[96:99], v[216:219], v[184:187], v[96:99]
	v_mfma_f32_16x16x32_f16 v[84:87], v[208:211], v[192:195], v[84:87]
	v_mfma_f32_16x16x32_f16 v[80:83], v[216:219], v[192:195], v[80:83]
	v_mfma_f32_16x16x32_f16 v[68:71], v[208:211], v[200:203], v[68:71]
	v_mfma_f32_16x16x32_f16 v[64:67], v[216:219], v[200:203], v[64:67]
	v_mfma_f32_16x16x32_f16 v[116:119], v[212:215], v[180:183], v[116:119]
	v_mfma_f32_16x16x32_f16 v[112:115], v[220:223], v[180:183], v[112:115]
	v_mfma_f32_16x16x32_f16 v[100:103], v[212:215], v[188:191], v[100:103]
	v_mfma_f32_16x16x32_f16 v[96:99], v[220:223], v[188:191], v[96:99]
	v_mfma_f32_16x16x32_f16 v[84:87], v[212:215], v[196:199], v[84:87]
	v_mfma_f32_16x16x32_f16 v[80:83], v[220:223], v[196:199], v[80:83]
	v_mfma_f32_16x16x32_f16 v[68:71], v[212:215], v[204:207], v[68:71]
	v_mfma_f32_16x16x32_f16 v[64:67], v[220:223], v[204:207], v[64:67]
	s_mov_b32 m0, s94
	v_lshl_add_u64 v[152:153], v[226:227], 0, s[28:29]
	s_barrier
	ds_read_b128 v[176:179], v160 offset:49152
	ds_read_b128 v[180:183], v160 offset:50176
	ds_read_b128 v[184:187], v160 offset:51200
	ds_read_b128 v[188:191], v160 offset:52224
	ds_read_b128 v[192:195], v160 offset:53248
	ds_read_b128 v[196:199], v160 offset:54272
	ds_read_b128 v[200:203], v160 offset:55296
	ds_read_b128 v[204:207], v160 offset:56320
	global_load_lds_dwordx4 v[152:153], off
	v_lshl_add_u64 v[152:153], v[228:229], 0, s[28:29]
	s_mov_b32 m0, s95
	s_nop 0
	global_load_lds_dwordx4 v[152:153], off
	s_barrier
; #define PG8_STAGE(bufoff, gbase, voff) do { _Pragma("unroll") for (int _i = 0; _i < 2; ++_i) \
;         __builtin_amdgcn_global_load_lds((const unsigned*)((const char*)(gbase) + (voff)[_i]), (LAS unsigned*)(lds + (bufoff) + ldsw + _i * 8192), 16, 0, 0); } while (0)
; #define PG8_MMA(ai, bj, At, Bt) do { __builtin_amdgcn_s_setprio(1); _Pragma("unroll") for (int m = 0; m < 4; ++m) _Pragma("unroll") for (int n = 0; n < 2; ++n) _Pragma("unroll") for (int k = 0; k < 2; ++k) \
;         acc[ai][bj][m][n] = __builtin_amdgcn_mfma_f32_16x16x32_f16(Bt[n][k], At[m][k], acc[ai][bj][m][n], 0, 0, 0); __builtin_amdgcn_s_setprio(0); } while (0)
; #define PG8_WAIT_V(n) asm volatile("s_waitcnt vmcnt(" #n ")" ::: "memory")
; #define PG8_WAIT_L(n) asm volatile("s_waitcnt lgkmcnt(" #n ")" ::: "memory")
; #define PG8_BAR __builtin_amdgcn_s_barrier()
; #define PG8_SCHED __builtin_amdgcn_sched_barrier(0)
; template <class Epi>
; __device__ __forceinline__ void gemm_phase(LAS unsigned char* lds, const Gemm g, const StaticOrder& S, const Epi& E) {
;     ...
;             PG8_BAR; PG8_WAIT_L(0); PG8_MMA(1, 0, At, B0); PG8_BAR; PG8_SCHED;
;             PG8_STAGE(PG8_SB(1, 1), b3 + hstep, voffB);
;             PG8_WAIT_V(6); PG8_BAR; PG8_MMA(1, 1, At, B1); PG8_BAR;
;     __device__ __forceinline__ void operator()(const f32x4 (&acc)[2][2][4][2], const pg8::Unit& u, int wr, int wc, int fr, int fq) const {
;     ...
;         } else {
; #pragma unroll
;             for (int ai = 0; ai < 2; ++ai)
; #pragma unroll
;                 for (int m = 0; m < 4; ++m) { const size_t r = (size_t)(row0 + ai * 128 + m * 16); float s1 = 0.f, s2 = 0.f;
; #pragma unroll
;                     for (int bj = 0; bj < 2; ++bj) { const int ch = 256 * (T - 24) + 128 * bj + 32 * wc + 8 * fq; h16x8 o;
; #pragma unroll
;                         for (int n = 0; n < 2; ++n) { const f32x4 v = acc[ai][bj][m][n];
; #pragma unroll
;                             for (int e = 0; e < 4; ++e) { o[4 * n + e] = (h16)v[e]; const float f = (float)o[4 * n + e]; s1 += f; s2 += f * f; } }
;                         *(h16x8*)(V + r * 1024 + ch) = o; }
;                     s1 += __shfl_xor(s1, 16); s2 += __shfl_xor(s2, 16); s1 += __shfl_xor(s1, 32); s2 += __shfl_xor(s2, 32);
;                     if (fq == 0) { atomicAdd(st + 2 * r, s1); atomicAdd(st + 2 * r + 1, s2); } }
	s_waitcnt lgkmcnt(0)
	s_waitcnt lgkmcnt(0)
	v_mfma_f32_16x16x32_f16 v[60:63], v[148:151], v[176:179], v[60:63]
	v_mfma_f32_16x16x32_f16 v[56:59], v[168:171], v[176:179], v[56:59]
	v_mfma_f32_16x16x32_f16 v[44:47], v[148:151], v[184:187], v[44:47]
	v_mfma_f32_16x16x32_f16 v[40:43], v[168:171], v[184:187], v[40:43]
	v_mfma_f32_16x16x32_f16 v[28:31], v[148:151], v[192:195], v[28:31]
	v_mfma_f32_16x16x32_f16 v[24:27], v[168:171], v[192:195], v[24:27]
	v_mfma_f32_16x16x32_f16 v[12:15], v[148:151], v[200:203], v[12:15]
	v_mfma_f32_16x16x32_f16 v[8:11], v[168:171], v[200:203], v[8:11]
	v_mfma_f32_16x16x32_f16 v[60:63], v[164:167], v[180:183], v[60:63]
	v_mfma_f32_16x16x32_f16 v[56:59], v[172:175], v[180:183], v[56:59]
	v_mfma_f32_16x16x32_f16 v[44:47], v[164:167], v[188:191], v[44:47]
	v_mfma_f32_16x16x32_f16 v[40:43], v[172:175], v[188:191], v[40:43]
	v_mfma_f32_16x16x32_f16 v[28:31], v[164:167], v[196:199], v[28:31]
	v_mfma_f32_16x16x32_f16 v[24:27], v[172:175], v[196:199], v[24:27]
	v_mfma_f32_16x16x32_f16 v[12:15], v[164:167], v[204:207], v[12:15]
	v_mfma_f32_16x16x32_f16 v[8:11], v[172:175], v[204:207], v[8:11]
	s_barrier
	s_add_u32 s34, s82, 0x40080
	s_addc_u32 s35, s83, 0
	s_add_i32 s82, s84, s87
	v_lshl_add_u64 v[148:149], s[34:35], 0, v[132:133]
	s_mov_b32 m0, s82
	s_nop 0
	global_load_lds_dwordx4 v[148:149], off
	v_lshl_add_u64 v[148:149], s[34:35], 0, v[136:137]
	s_add_i32 m0, s82, 0x2000
	s_nop 0
	global_load_lds_dwordx4 v[148:149], off
	s_waitcnt vmcnt(6)
	s_barrier
	v_mfma_f32_16x16x32_f16 v[52:55], v[208:211], v[176:179], v[52:55]
	v_mfma_f32_16x16x32_f16 v[48:51], v[216:219], v[176:179], v[48:51]
	v_mfma_f32_16x16x32_f16 v[36:39], v[208:211], v[184:187], v[36:39]
	v_mfma_f32_16x16x32_f16 v[32:35], v[216:219], v[184:187], v[32:35]
	v_mfma_f32_16x16x32_f16 v[20:23], v[208:211], v[192:195], v[20:23]
	v_mfma_f32_16x16x32_f16 v[16:19], v[216:219], v[192:195], v[16:19]
	v_mfma_f32_16x16x32_f16 v[4:7], v[208:211], v[200:203], v[4:7]
	v_mfma_f32_16x16x32_f16 v[0:3], v[216:219], v[200:203], v[0:3]
	v_mfma_f32_16x16x32_f16 v[52:55], v[212:215], v[180:183], v[52:55]
	v_mfma_f32_16x16x32_f16 v[48:51], v[220:223], v[180:183], v[48:51]
	v_mfma_f32_16x16x32_f16 v[36:39], v[212:215], v[188:191], v[36:39]
	v_mfma_f32_16x16x32_f16 v[32:35], v[220:223], v[188:191], v[32:35]
	v_mfma_f32_16x16x32_f16 v[20:23], v[212:215], v[196:199], v[20:23]
	v_mfma_f32_16x16x32_f16 v[16:19], v[220:223], v[196:199], v[16:19]
	v_mfma_f32_16x16x32_f16 v[4:7], v[212:215], v[204:207], v[4:7]
	v_mfma_f32_16x16x32_f16 v[0:3], v[220:223], v[204:207], v[0:3]
	s_add_i32 s15, s15, 2
	s_add_u32 s80, s80, 0x100
	s_addc_u32 s81, s81, 0
	s_add_u32 vcc_hi, vcc_hi, 0x100
	s_addc_u32 s14, s14, 0
	s_cmp_gt_u32 s15, 13
	s_barrier
	s_cbranch_scc0 .LBB0_195
	v_lshl_add_u32 v148, s78, 8, v154
	s_cmp_gt_i32 s76, 15
	s_mov_b64 s[78:79], -1
	s_cbranch_scc0 .LBB0_218
	s_cmp_lt_u32 s76, 24
	s_cbranch_scc1 .LBB0_215
	v_and_b32_e32 v150, 64, v162
	v_xor_b32_e32 v149, 16, v162
	v_add_u32_e32 v150, 64, v150
	v_cmp_lt_i32_e32 vcc, v149, v150
	v_cvt_f16_f32_e32 v163, v124
	v_cvt_f16_f32_e32 v166, v126
	v_cndmask_b32_e32 v149, v162, v149, vcc
	v_lshlrev_b32_e32 v152, 2, v149
	v_xor_b32_e32 v149, 32, v162
	v_cmp_lt_i32_e32 vcc, v149, v150
	v_cvt_f16_f32_e32 v150, v125
	v_cvt_f32_f16_e32 v164, v163
	v_cvt_f16_f32_e32 v167, v127
	v_cvt_f32_f16_e32 v168, v166
	v_cvt_f32_f16_e32 v165, v150
	v_add_f32_e32 v164, 0, v164
	v_cvt_f16_f32_e32 v169, v122
	v_cvt_f16_f32_e32 v170, v123
	v_add_f32_e32 v164, v164, v165
	v_mul_f32_e32 v165, v165, v165
	v_fma_mix_f32 v163, v163, v163, v165 op_sel_hi:[1,1,0]
	v_cvt_f32_f16_e32 v165, v167
	v_add_f32_e32 v164, v164, v168
	v_cvt_f16_f32_e32 v168, v120
	v_fma_mix_f32 v163, v166, v166, v163 op_sel_hi:[1,1,0]
	v_add_f32_e32 v164, v164, v165
	v_cvt_f16_f32_e32 v165, v121
	v_cvt_f32_f16_e32 v166, v168
	v_fma_mix_f32 v163, v167, v167, v163 op_sel_hi:[1,1,0]
	v_cvt_f16_f32_e32 v171, v116
	v_cvt_f32_f16_e32 v167, v165
	v_fma_mix_f32 v163, v168, v168, v163 op_sel_hi:[1,1,0]
	v_add_f32_e32 v164, v164, v166
	v_cvt_f32_f16_e32 v166, v169
	v_fma_mix_f32 v163, v165, v165, v163 op_sel_hi:[1,1,0]
	v_add_f32_e32 v164, v164, v167
	v_fma_mix_f32 v163, v169, v169, v163 op_sel_hi:[1,1,0]
	v_cvt_f32_f16_e32 v169, v170
	v_add_f32_e32 v168, v164, v166
	v_cvt_f32_f16_e32 v172, v171
	v_fma_mix_f32 v163, v170, v170, v163 op_sel_hi:[1,1,0]
	v_add_f32_e32 v168, v168, v169
	v_cvt_f16_f32_e32 v169, v117
	v_add_f32_e32 v168, v168, v172
	v_cvt_f16_f32_e32 v172, v118
	v_fma_mix_f32 v163, v171, v171, v163 op_sel_hi:[1,1,0]
	v_cvt_f32_f16_e32 v170, v169
	v_fma_mix_f32 v163, v169, v169, v163 op_sel_hi:[1,1,0]
	v_cvt_f32_f16_e32 v171, v172
	v_cvt_f16_f32_e32 v169, v112
	v_add_f32_e32 v168, v168, v170
	v_cvt_f16_f32_e32 v170, v119
	v_add_f32_e32 v168, v168, v171
	v_fma_mix_f32 v163, v172, v172, v163 op_sel_hi:[1,1,0]
	v_cvt_f32_f16_e32 v171, v169
	v_cvt_f32_f16_e32 v173, v170
	v_cvt_f16_f32_e32 v172, v113
	v_fma_mix_f32 v163, v170, v170, v163 op_sel_hi:[1,1,0]
	v_cvt_f16_f32_e32 v170, v114
	v_add_f32_e32 v168, v168, v173
	v_add_f32_e32 v168, v168, v171
	v_cvt_f32_f16_e32 v171, v172
	v_cvt_f16_f32_e32 v173, v115
	v_fma_mix_f32 v163, v169, v169, v163 op_sel_hi:[1,1,0]
	v_cvt_f32_f16_e32 v169, v170
	v_add_f32_e32 v168, v168, v171
	v_cvt_f32_f16_e32 v171, v173
	v_fma_mix_f32 v163, v172, v172, v163 op_sel_hi:[1,1,0]
	v_add_f32_e32 v168, v168, v169
	v_fma_mix_f32 v163, v170, v170, v163 op_sel_hi:[1,1,0]
	v_add_f32_e32 v168, v168, v171
	v_fma_mix_f32 v163, v173, v173, v163 op_sel_hi:[1,1,0]
	ds_bpermute_b32 v172, v152, v168
	ds_bpermute_b32 v173, v152, v163
	v_cndmask_b32_e32 v149, v162, v149, vcc
	v_lshlrev_b32_e32 v153, 2, v149
	v_ashrrev_i32_e32 v149, 31, v148
	v_lshlrev_b64 v[150:151], 11, v[148:149]
	v_lshl_add_u32 v138, s76, 8, v156
	v_lshl_add_u64 v[150:151], s[18:19], 0, v[150:151]
	v_cvt_pk_f16_f32 v167, v122, v123
	v_cvt_pk_f16_f32 v166, v120, v121
	v_cvt_pk_f16_f32 v165, v126, v127
	v_cvt_pk_f16_f32 v164, v124, v125
	v_lshl_add_u64 v[170:171], v[138:139], 1, v[150:151]
	s_waitcnt lgkmcnt(0)
	v_add_f32_e32 v150, v168, v172
	v_add_f32_e32 v151, v163, v173
	global_store_dwordx4 v[170:171], v[164:167], off
	ds_bpermute_b32 v163, v153, v150
	ds_bpermute_b32 v164, v153, v151
	v_cvt_pk_f16_f32 v169, v114, v115
	v_cvt_pk_f16_f32 v168, v112, v113
	v_cvt_pk_f16_f32 v167, v118, v119
	v_cvt_pk_f16_f32 v166, v116, v117
	global_store_dwordx4 v[170:171], v[166:169], off offset:256
	s_and_saveexec_b64 s[78:79], s[0:1]
	s_cbranch_execz .LBB0_200
	v_lshl_add_u64 v[166:167], v[148:149], 3, s[20:21]
	s_waitcnt lgkmcnt(0)
	v_add_f32_e32 v149, v150, v163
	v_add_f32_e32 v150, v151, v164
	global_atomic_add_f32 v[166:167], v149, off
	global_atomic_add_f32 v[166:167], v150, off offset:4

; #define PG8_BAR __builtin_amdgcn_s_barrier()
; template <class Epi>
; __device__ __forceinline__ void gemm_phase(LAS unsigned char* lds, const Gemm g, const StaticOrder& S, const Epi& E) {
;     ...
;     if (wr == 0) PG8_BAR;
;     PG8_BAR;
.LBB0_222:
	s_barrier
	s_setprio 0

; #define LAS __attribute__((address_space(3)))
; #define PG8_BAR __builtin_amdgcn_s_barrier()
;     __host__ __device__ bool next(int i, Unit& u) const {
;         const long L = (long)i * G + c; if (L >= nwg) return false;
;         int wgid = (int)L; { const int q = nwg / NXCD, r = nwg % NXCD, xcd = wgid % NXCD, off = wgid / NXCD; wgid = (xcd < r ? xcd * (q + 1) : r * (q + 1) + (xcd - r) * q) + off; }
;         const int nig = WGM * nN, gid = wgid / nig, fm = gid * WGM, gsz = (nM - fm) < WGM ? (nM - fm) : WGM;
;         u.pm = fm + ((wgid % nig) % gsz); u.pn = (wgid % nig) / gsz; return true;
;     }
; template <class Epi>
; __device__ __forceinline__ void gemm_phase(LAS unsigned char* lds, const Gemm g, const StaticOrder& S, const Epi& E) {
;     const int tid = threadIdx.x, wid = __builtin_amdgcn_readfirstlane(tid >> 6), lane = tid & 63, wr = wid >> 2, wc = wid & 3, fr = lane & 15, fq = lane >> 4;
;     const int K = g.K, nt = K / BK;
;     unsigned voffA[2], voffB[2];
; #pragma unroll
;     for (int i = 0; i < 2; ++i) { int R, C; stage_rc(tid * 16 + i * 8192, R, C); const int Rb = Epi::PERM ? ((R & ~31) + perm32(R & 31)) : R; voffA[i] = (unsigned)(R * K + C) * 2u; voffB[i] = (unsigned)(Rb * K + C) * 2u; }
;     const size_t kstep = (size_t)(BK * 2);
;     const size_t hstep = (size_t)HALF * K * 2;
;     const size_t tstep = 2 * hstep;
;     const unsigned ldsw = (unsigned)wid * 1024u;
;     const int aoff = lds_byte(wr * 64 + fr, fq * 8), boff = lds_byte(wc * 32 + fr, fq * 8);
;     ...
;     Unit cur, nxt; int ui = 0;
;     if (!S.next(0, cur)) return;
;     f32x4 acc[2][2][4][2];
; #pragma unroll
;     for (int a = 0; a < 2; ++a)
; #pragma unroll
;         for (int b = 0; b < 2; ++b)
; #pragma unroll
;             for (int m = 0; m < 4; ++m)
; #pragma unroll
;                 for (int n = 0; n < 2; ++n) acc[a][b][m][n] = (f32x4){0.f, 0.f, 0.f, 0.f};
;     h16x8 At[4][2], B0[2][2], B1[2][2];
;     const char* cA = (const char*)g.A + (size_t)cur.pm * tstep; const char* cB = (const char*)g.Bt + (size_t)cur.pn * tstep;
;     PG8_STAGE(PG8_SB(0, 0), cB, voffB); PG8_STAGE(PG8_SA(0, 0), cA, voffA); PG8_STAGE(PG8_SB(0, 1), cB + hstep, voffB); PG8_STAGE(PG8_SA(0, 1), cA + hstep, voffA);
;     if (wr == 1) PG8_BAR;
.LBB0_344:
	s_cmp_lt_i32 s72, 5
	s_cselect_b64 s[4:5], -1, 0
	s_and_b64 s[4:5], s[4:5], s[0:1]
	s_andn2_b64 vcc, exec, s[4:5]
	s_cbranch_vccnz .LBB0_361
	s_cmpk_gt_i32 s2, 0xff
	v_readfirstlane_b32 s33, v130
	s_cbranch_scc1 .LBB0_361
	v_lshrrev_b32_e32 v2, 1, v130
	v_and_b32_e32 v11, 24, v2
	v_lshrrev_b32_e32 v2, 5, v130
	v_and_b32_e32 v2, 4, v2
	v_bfe_u32 v3, v130, 2, 2
	s_waitcnt lgkmcnt(0)
	s_add_u32 s56, s70, 0xa400000
	v_lshlrev_b32_e32 v0, 4, v130
	v_and_b32_e32 v1, 32, v130
	v_bfe_u32 v10, v130, 2, 4
	v_or3_b32 v2, v2, v3, v11
	v_lshrrev_b32_e32 v3, 3, v130
	s_movk_i32 s0, 0x70
	s_addc_u32 s57, s71, 0
	v_bitop3_b32 v8, v0, v1, 48 bitop3:0x6c
	v_and_b32_e32 v9, 64, v130
	v_and_or_b32 v4, v3, s0, v10
	s_movk_i32 s0, 0x60
	v_add_u32_e32 v12, 0x2000, v0
	s_add_u32 s76, s70, 0xe00000
	v_or_b32_e32 v1, v8, v9
	v_and_or_b32 v3, v3, s0, v2
	v_lshrrev_b32_e32 v0, 7, v12
	s_movk_i32 s0, 0xf0
	s_addc_u32 s77, s71, 0
	v_lshl_or_b32 v132, v3, 12, v1
	v_and_or_b32 v3, v0, s0, v10
	s_movk_i32 s0, 0xe0
	s_ashr_i32 s79, s2, 31
	v_and_or_b32 v0, v0, s0, v2
	s_lshr_b32 s0, s79, 29
	s_add_i32 s0, s2, s0
	s_and_b32 s6, s0, -8
	s_lshr_b32 s8, s33, 6
	s_sub_i32 s6, s2, s6
	s_lshr_b32 s1, s33, 8
	s_lshl_b32 s78, s8, 10
	s_lshl_b32 s9, s6, 5
	s_ashr_i32 s0, s0, 3
	s_mul_i32 s7, s6, 33
	s_cmp_lt_i32 s6, 0
	s_cselect_b32 s6, s7, s9
	s_add_i32 s0, s6, s0
	s_ashr_i32 s6, s0, 31
	s_lshr_b32 s6, s6, 27
	s_add_i32 s6, s0, s6
	s_ashr_i32 s7, s6, 5
	s_andn2_b32 s6, s6, 31
	s_sub_i32 s6, s0, s6
	s_bfe_i32 s0, s6, 0x80000
	s_bfe_u32 s0, s0, 0x3000c
	s_add_i32 s9, s6, s0
	s_bfe_i32 s0, s9, 0x80000
	s_and_b32 s9, s9, 0xf8
	s_sub_i32 s6, s6, s9
	s_lshl_b32 s7, s7, 3
	s_sext_i32_i16 s0, s0
	s_sext_i32_i8 s6, s6
	s_lshr_b32 s0, s0, 3
	s_add_i32 s22, s7, s6
	s_ashr_i32 s23, s22, 31
	s_bfe_i64 s[10:11], s[0:1], 0x100000
	s_lshl_b64 s[6:7], s[22:23], 20
	s_lshl_b64 s[10:11], s[10:11], 20
	s_add_u32 s48, s76, s10
	s_addc_u32 s49, s77, s11
	s_add_i32 s23, s78, 0
	s_add_i32 m0, s23, 0x10000
	v_lshl_or_b32 v136, v0, 12, v1
	global_load_lds_dwordx4 v132, s[48:49]
	s_add_i32 m0, s23, 0x12000
	s_add_u32 s46, s56, s6
	v_lshl_or_b32 v128, v4, 12, v1
	global_load_lds_dwordx4 v136, s[48:49]
	s_addc_u32 s47, s57, s7
	s_mov_b32 m0, s23
	s_add_i32 s80, s23, 0x2000
	v_lshl_or_b32 v134, v3, 12, v1
	global_load_lds_dwordx4 v128, s[46:47]
	s_mov_b32 m0, s80
	s_add_u32 s6, s48, 0x80000
	global_load_lds_dwordx4 v134, s[46:47]
	s_addc_u32 s7, s49, 0
	s_add_i32 m0, s23, 0x14000
	v_mov_b32_e32 v133, 0
	global_load_lds_dwordx4 v132, s[6:7]
	s_add_i32 m0, s23, 0x16000
	v_mov_b32_e32 v137, v133
	global_load_lds_dwordx4 v136, s[6:7]
	s_add_u32 s6, s46, 0x80000
	s_addc_u32 s7, s47, 0
	s_add_i32 s81, s23, 0x4000
	s_mov_b32 m0, s81
	s_add_i32 s82, s23, 0x6000
	global_load_lds_dwordx4 v128, s[6:7]
	s_mov_b32 m0, s82
	v_mov_b32_e32 v129, v133
	global_load_lds_dwordx4 v134, s[6:7]
	v_mov_b32_e32 v135, v133
	s_mov_b32 s83, 0
	v_lshl_add_u64 v[6:7], s[48:49], 0, v[132:133]
	v_lshl_add_u64 v[4:5], s[48:49], 0, v[136:137]
	v_lshl_add_u64 v[2:3], s[46:47], 0, v[128:129]
	s_cmp_lg_u32 s1, 1
	v_lshl_add_u64 v[0:1], s[46:47], 0, v[134:135]
	s_cbranch_scc1 .LBB0_348
	s_barrier
	s_setprio 1

; #define PG8_STAGE(bufoff, gbase, voff) do { _Pragma("unroll") for (int _i = 0; _i < 2; ++_i) \
;         __builtin_amdgcn_global_load_lds((const unsigned*)((const char*)(gbase) + (voff)[_i]), (LAS unsigned*)(lds + (bufoff) + ldsw + _i * 8192), 16, 0, 0); } while (0)
; #define PG8_LDA(dst, b, h) do { _Pragma("unroll") for (int m = 0; m < 4; ++m) _Pragma("unroll") for (int k = 0; k < 2; ++k) dst[m][k] = *(const LAS h16x8*)(lds + PG8_SA(b, h) + aoff + m * 2048 + k * 1024); } while (0)
; #define PG8_LDB(dst, b, h) do { _Pragma("unroll") for (int n = 0; n < 2; ++n) _Pragma("unroll") for (int k = 0; k < 2; ++k) dst[n][k] = *(const LAS h16x8*)(lds + PG8_SB(b, h) + boff + n * 2048 + k * 1024); } while (0)
; #define PG8_MMA(ai, bj, At, Bt) do { __builtin_amdgcn_s_setprio(1); _Pragma("unroll") for (int m = 0; m < 4; ++m) _Pragma("unroll") for (int n = 0; n < 2; ++n) _Pragma("unroll") for (int k = 0; k < 2; ++k) \
;         acc[ai][bj][m][n] = __builtin_amdgcn_mfma_f32_16x16x32_f16(Bt[n][k], At[m][k], acc[ai][bj][m][n], 0, 0, 0); __builtin_amdgcn_s_setprio(0); } while (0)
; #define PG8_WAIT_L(n) asm volatile("s_waitcnt lgkmcnt(" #n ")" ::: "memory")
; #define PG8_BAR __builtin_amdgcn_s_barrier()
; #define PG8_SCHED __builtin_amdgcn_sched_barrier(0)
; template <class Epi>
; __device__ __forceinline__ void gemm_phase(LAS unsigned char* lds, const Gemm g, const StaticOrder& S, const Epi& E) {
;     ...
;             PG8_LDB(B0, 0, 0); PG8_SCHED; PG8_LDA(At, 0, 0); PG8_STAGE(PG8_SA(1, 1), a1 + hstep, voffA);
;             PG8_WAIT_L(8); PG8_BAR; PG8_WAIT_L(0); PG8_MMA(0, 0, At, B0); PG8_BAR; PG8_SCHED;
;             PG8_LDB(B1, 0, 1); PG8_STAGE(PG8_SB(0, 0), b2, voffB);
;             PG8_BAR; PG8_WAIT_L(0); PG8_MMA(0, 1, At, B1); PG8_BAR;
;             PG8_LDA(At, 0, 1); PG8_STAGE(PG8_SA(0, 0), a2, voffA);
;             PG8_BAR; PG8_WAIT_L(0); PG8_MMA(1, 0, At, B0); PG8_BAR; PG8_SCHED;
;             PG8_STAGE(PG8_SB(0, 1), b2 + hstep, voffB);
.LBB0_356:
	ds_read_b128 v[152:155], v149
	ds_read_b128 v[156:159], v149 offset:1024
	ds_read_b128 v[160:163], v149 offset:2048
	ds_read_b128 v[164:167], v149 offset:3072
	s_add_u32 s34, s46, 0xfff80080
	s_addc_u32 s35, s47, -1
	s_cmp_eq_u32 s15, 28
	s_cselect_b32 s53, s27, s35
	s_cselect_b32 s52, s94, s34
	s_cselect_b32 s49, s25, s14
	s_cselect_b32 s48, s95, s96
	v_lshl_add_u64 v[202:203], s[46:47], 0, v[138:139]
	s_add_i32 m0, s23, 0xc000
	ds_read_b128 v[170:173], v150
	ds_read_b128 v[174:177], v150 offset:1024
	ds_read_b128 v[178:181], v150 offset:2048
	ds_read_b128 v[182:185], v150 offset:3072
	ds_read_b128 v[186:189], v150 offset:4096
	ds_read_b128 v[190:193], v150 offset:5120
	ds_read_b128 v[194:197], v150 offset:6144
	ds_read_b128 v[198:201], v150 offset:7168
	global_load_lds_dwordx4 v[202:203], off
	v_lshl_add_u64 v[202:203], s[46:47], 0, v[140:141]
	s_add_i32 m0, s23, 0xe000
	s_nop 0
	global_load_lds_dwordx4 v[202:203], off
	s_waitcnt lgkmcnt(8)
	s_barrier
	s_waitcnt lgkmcnt(0)
	s_waitcnt lgkmcnt(0)
	v_mfma_f32_16x16x32_f16 v[124:127], v[152:155], v[170:173], v[124:127]
	v_mfma_f32_16x16x32_f16 v[120:123], v[160:163], v[170:173], v[120:123]
	v_mfma_f32_16x16x32_f16 v[116:119], v[152:155], v[178:181], v[116:119]
	v_mfma_f32_16x16x32_f16 v[112:115], v[160:163], v[178:181], v[112:115]
	v_mfma_f32_16x16x32_f16 v[100:103], v[152:155], v[186:189], v[100:103]
	v_mfma_f32_16x16x32_f16 v[96:99], v[160:163], v[186:189], v[96:99]
	v_mfma_f32_16x16x32_f16 v[84:87], v[152:155], v[194:197], v[84:87]
	v_mfma_f32_16x16x32_f16 v[80:83], v[160:163], v[194:197], v[80:83]
	v_mfma_f32_16x16x32_f16 v[124:127], v[156:159], v[174:177], v[124:127]
	v_mfma_f32_16x16x32_f16 v[120:123], v[164:167], v[174:177], v[120:123]
	v_mfma_f32_16x16x32_f16 v[116:119], v[156:159], v[182:185], v[116:119]
	v_mfma_f32_16x16x32_f16 v[112:115], v[164:167], v[182:185], v[112:115]
	v_mfma_f32_16x16x32_f16 v[100:103], v[156:159], v[190:193], v[100:103]
	v_mfma_f32_16x16x32_f16 v[96:99], v[164:167], v[190:193], v[96:99]
	v_mfma_f32_16x16x32_f16 v[84:87], v[156:159], v[198:201], v[84:87]
	v_mfma_f32_16x16x32_f16 v[80:83], v[164:167], v[198:201], v[80:83]
	s_barrier
	s_add_i32 s34, s88, s78
	v_lshl_add_u64 v[218:219], s[48:49], 0, v[132:133]
	s_mov_b32 m0, s34
	ds_read_b128 v[202:205], v151
	ds_read_b128 v[206:209], v151 offset:1024
	ds_read_b128 v[210:213], v151 offset:2048
	ds_read_b128 v[214:217], v151 offset:3072
	global_load_lds_dwordx4 v[218:219], off
	v_lshl_add_u64 v[220:221], s[48:49], 0, v[136:137]
	s_add_i32 m0, s34, 0x2000
	s_nop 0
	global_load_lds_dwordx4 v[220:221], off
	s_barrier
	s_waitcnt lgkmcnt(0)
	s_waitcnt lgkmcnt(0)
	v_mfma_f32_16x16x32_f16 v[108:111], v[202:205], v[170:173], v[108:111]
	v_mfma_f32_16x16x32_f16 v[104:107], v[210:213], v[170:173], v[104:107]
	v_mfma_f32_16x16x32_f16 v[92:95], v[202:205], v[178:181], v[92:95]
	v_mfma_f32_16x16x32_f16 v[88:91], v[210:213], v[178:181], v[88:91]
	v_mfma_f32_16x16x32_f16 v[76:79], v[202:205], v[186:189], v[76:79]
	v_mfma_f32_16x16x32_f16 v[72:75], v[210:213], v[186:189], v[72:75]
	v_mfma_f32_16x16x32_f16 v[68:71], v[202:205], v[194:197], v[68:71]
	v_mfma_f32_16x16x32_f16 v[64:67], v[210:213], v[194:197], v[64:67]
	v_mfma_f32_16x16x32_f16 v[108:111], v[206:209], v[174:177], v[108:111]
	v_mfma_f32_16x16x32_f16 v[104:107], v[214:217], v[174:177], v[104:107]
	v_mfma_f32_16x16x32_f16 v[92:95], v[206:209], v[182:185], v[92:95]
	v_mfma_f32_16x16x32_f16 v[88:91], v[214:217], v[182:185], v[88:91]
	v_mfma_f32_16x16x32_f16 v[76:79], v[206:209], v[190:193], v[76:79]
	v_mfma_f32_16x16x32_f16 v[72:75], v[214:217], v[190:193], v[72:75]
	v_mfma_f32_16x16x32_f16 v[68:71], v[206:209], v[198:201], v[68:71]
	v_mfma_f32_16x16x32_f16 v[64:67], v[214:217], v[198:201], v[64:67]
	s_mov_b32 m0, s23
	v_lshl_add_u64 v[222:223], s[52:53], 0, v[128:129]
	s_barrier
	ds_read_b128 v[170:173], v150 offset:16384
	ds_read_b128 v[174:177], v150 offset:17408
	ds_read_b128 v[178:181], v150 offset:18432
	ds_read_b128 v[182:185], v150 offset:19456
	ds_read_b128 v[186:189], v150 offset:20480
	ds_read_b128 v[190:193], v150 offset:21504
	ds_read_b128 v[194:197], v150 offset:22528
	ds_read_b128 v[198:201], v150 offset:23552
	global_load_lds_dwordx4 v[222:223], off
	v_lshl_add_u64 v[224:225], s[52:53], 0, v[134:135]
	s_mov_b32 m0, s80
	s_nop 0
	global_load_lds_dwordx4 v[224:225], off
	s_barrier
	s_waitcnt lgkmcnt(0)
	s_waitcnt lgkmcnt(0)
	v_mfma_f32_16x16x32_f16 v[60:63], v[152:155], v[170:173], v[60:63]
	v_mfma_f32_16x16x32_f16 v[56:59], v[160:163], v[170:173], v[56:59]
	v_mfma_f32_16x16x32_f16 v[52:55], v[152:155], v[178:181], v[52:55]
	v_mfma_f32_16x16x32_f16 v[48:51], v[160:163], v[178:181], v[48:51]
	v_mfma_f32_16x16x32_f16 v[36:39], v[152:155], v[186:189], v[36:39]
	v_mfma_f32_16x16x32_f16 v[32:35], v[160:163], v[186:189], v[32:35]
	v_mfma_f32_16x16x32_f16 v[20:23], v[152:155], v[194:197], v[20:23]
	v_mfma_f32_16x16x32_f16 v[16:19], v[160:163], v[194:197], v[16:19]
	v_mfma_f32_16x16x32_f16 v[60:63], v[156:159], v[174:177], v[60:63]
	v_mfma_f32_16x16x32_f16 v[56:59], v[164:167], v[174:177], v[56:59]
	v_mfma_f32_16x16x32_f16 v[52:55], v[156:159], v[182:185], v[52:55]
	v_mfma_f32_16x16x32_f16 v[48:51], v[164:167], v[182:185], v[48:51]
	v_mfma_f32_16x16x32_f16 v[36:39], v[156:159], v[190:193], v[36:39]
	v_mfma_f32_16x16x32_f16 v[32:35], v[164:167], v[190:193], v[32:35]
	v_mfma_f32_16x16x32_f16 v[20:23], v[156:159], v[198:201], v[20:23]
	v_mfma_f32_16x16x32_f16 v[16:19], v[164:167], v[198:201], v[16:19]
	s_barrier
; #define PG8_STAGE(bufoff, gbase, voff) do { _Pragma("unroll") for (int _i = 0; _i < 2; ++_i) \
;         __builtin_amdgcn_global_load_lds((const unsigned*)((const char*)(gbase) + (voff)[_i]), (LAS unsigned*)(lds + (bufoff) + ldsw + _i * 8192), 16, 0, 0); } while (0)
; #define PG8_LDA(dst, b, h) do { _Pragma("unroll") for (int m = 0; m < 4; ++m) _Pragma("unroll") for (int k = 0; k < 2; ++k) dst[m][k] = *(const LAS h16x8*)(lds + PG8_SA(b, h) + aoff + m * 2048 + k * 1024); } while (0)
; #define PG8_LDB(dst, b, h) do { _Pragma("unroll") for (int n = 0; n < 2; ++n) _Pragma("unroll") for (int k = 0; k < 2; ++k) dst[n][k] = *(const LAS h16x8*)(lds + PG8_SB(b, h) + boff + n * 2048 + k * 1024); } while (0)
; #define PG8_MMA(ai, bj, At, Bt) do { __builtin_amdgcn_s_setprio(1); _Pragma("unroll") for (int m = 0; m < 4; ++m) _Pragma("unroll") for (int n = 0; n < 2; ++n) _Pragma("unroll") for (int k = 0; k < 2; ++k) \
;         acc[ai][bj][m][n] = __builtin_amdgcn_mfma_f32_16x16x32_f16(Bt[n][k], At[m][k], acc[ai][bj][m][n], 0, 0, 0); __builtin_amdgcn_s_setprio(0); } while (0)
; #define PG8_WAIT_V(n) asm volatile("s_waitcnt vmcnt(" #n ")" ::: "memory")
; #define PG8_WAIT_L(n) asm volatile("s_waitcnt lgkmcnt(" #n ")" ::: "memory")
; #define PG8_BAR __builtin_amdgcn_s_barrier()
; #define PG8_SCHED __builtin_amdgcn_sched_barrier(0)
; template <class Epi>
; __device__ __forceinline__ void gemm_phase(LAS unsigned char* lds, const Gemm g, const StaticOrder& S, const Epi& E) {
;     ...
;             PG8_STAGE(PG8_SB(0, 1), b2 + hstep, voffB);
;             PG8_WAIT_V(6); PG8_BAR; PG8_MMA(1, 1, At, B1); PG8_BAR;
;             PG8_LDB(B0, 1, 0); PG8_SCHED; PG8_LDA(At, 1, 0); PG8_STAGE(PG8_SA(0, 1), a2 + hstep, voffA);
;             PG8_WAIT_L(8); PG8_BAR; PG8_WAIT_L(0); PG8_MMA(0, 0, At, B0); PG8_BAR; PG8_SCHED;
;             PG8_LDB(B1, 1, 1); PG8_STAGE(PG8_SB(1, 0), b3, voffB);
;             PG8_BAR; PG8_WAIT_L(0); PG8_MMA(0, 1, At, B1); PG8_BAR;
;             PG8_LDA(At, 1, 1); PG8_STAGE(PG8_SA(1, 0), a3, voffA);
;             PG8_BAR; PG8_WAIT_L(0); PG8_MMA(1, 0, At, B0); PG8_BAR; PG8_SCHED;
	s_add_u32 s34, s48, 0x80000
	s_addc_u32 s35, s49, 0
	s_add_i32 s97, s89, s78
	v_lshl_add_u64 v[152:153], s[34:35], 0, v[132:133]
	s_mov_b32 m0, s97
	s_nop 0
	global_load_lds_dwordx4 v[152:153], off
	v_lshl_add_u64 v[152:153], s[34:35], 0, v[136:137]
	s_add_i32 m0, s97, 0x2000
	s_nop 0
	global_load_lds_dwordx4 v[152:153], off
	s_waitcnt vmcnt(6)
	s_barrier
	v_mfma_f32_16x16x32_f16 v[44:47], v[202:205], v[170:173], v[44:47]
	v_mfma_f32_16x16x32_f16 v[40:43], v[210:213], v[170:173], v[40:43]
	v_mfma_f32_16x16x32_f16 v[28:31], v[202:205], v[178:181], v[28:31]
	v_mfma_f32_16x16x32_f16 v[24:27], v[210:213], v[178:181], v[24:27]
	v_mfma_f32_16x16x32_f16 v[12:15], v[202:205], v[186:189], v[12:15]
	v_mfma_f32_16x16x32_f16 v[8:11], v[210:213], v[186:189], v[8:11]
	v_mfma_f32_16x16x32_f16 v[4:7], v[202:205], v[194:197], v[4:7]
	v_mfma_f32_16x16x32_f16 v[0:3], v[210:213], v[194:197], v[0:3]
	v_mfma_f32_16x16x32_f16 v[44:47], v[206:209], v[174:177], v[44:47]
	v_mfma_f32_16x16x32_f16 v[40:43], v[214:217], v[174:177], v[40:43]
	v_mfma_f32_16x16x32_f16 v[28:31], v[206:209], v[182:185], v[28:31]
	v_mfma_f32_16x16x32_f16 v[24:27], v[214:217], v[182:185], v[24:27]
	v_mfma_f32_16x16x32_f16 v[12:15], v[206:209], v[190:193], v[12:15]
	v_mfma_f32_16x16x32_f16 v[8:11], v[214:217], v[190:193], v[8:11]
	v_mfma_f32_16x16x32_f16 v[4:7], v[206:209], v[198:201], v[4:7]
	v_mfma_f32_16x16x32_f16 v[0:3], v[214:217], v[198:201], v[0:3]
	s_add_i32 s97, 0, 0x18000
	v_add_u32_e32 v164, s97, v147
	s_barrier
	ds_read_b128 v[152:155], v164
	ds_read_b128 v[156:159], v164 offset:1024
	ds_read_b128 v[160:163], v164 offset:2048
	ds_read_b128 v[164:167], v164 offset:3072
	s_add_u32 s34, s52, 0x80000
	s_addc_u32 s35, s53, 0
	s_mov_b32 m0, s81
	v_lshl_add_u64 v[202:203], s[34:35], 0, v[128:129]
	ds_read_b128 v[170:173], v150 offset:32768
	ds_read_b128 v[174:177], v150 offset:33792
	ds_read_b128 v[178:181], v150 offset:34816
	ds_read_b128 v[182:185], v150 offset:35840
	ds_read_b128 v[186:189], v150 offset:36864
	ds_read_b128 v[190:193], v150 offset:37888
	ds_read_b128 v[194:197], v150 offset:38912
	ds_read_b128 v[198:201], v150 offset:39936
	global_load_lds_dwordx4 v[202:203], off
	v_lshl_add_u64 v[202:203], s[34:35], 0, v[134:135]
	s_mov_b32 m0, s82
	s_nop 0
	global_load_lds_dwordx4 v[202:203], off
	s_waitcnt lgkmcnt(8)
	s_barrier
	s_waitcnt lgkmcnt(0)
	s_waitcnt lgkmcnt(0)
	v_mfma_f32_16x16x32_f16 v[124:127], v[152:155], v[170:173], v[124:127]
	v_mfma_f32_16x16x32_f16 v[120:123], v[160:163], v[170:173], v[120:123]
	v_mfma_f32_16x16x32_f16 v[116:119], v[152:155], v[178:181], v[116:119]
	v_mfma_f32_16x16x32_f16 v[112:115], v[160:163], v[178:181], v[112:115]
	v_mfma_f32_16x16x32_f16 v[100:103], v[152:155], v[186:189], v[100:103]
	v_mfma_f32_16x16x32_f16 v[96:99], v[160:163], v[186:189], v[96:99]
	v_mfma_f32_16x16x32_f16 v[84:87], v[152:155], v[194:197], v[84:87]
	v_mfma_f32_16x16x32_f16 v[80:83], v[160:163], v[194:197], v[80:83]
	v_mfma_f32_16x16x32_f16 v[124:127], v[156:159], v[174:177], v[124:127]
	v_mfma_f32_16x16x32_f16 v[120:123], v[164:167], v[174:177], v[120:123]
	v_mfma_f32_16x16x32_f16 v[116:119], v[156:159], v[182:185], v[116:119]
	v_mfma_f32_16x16x32_f16 v[112:115], v[164:167], v[182:185], v[112:115]
	v_mfma_f32_16x16x32_f16 v[100:103], v[156:159], v[190:193], v[100:103]
	v_mfma_f32_16x16x32_f16 v[96:99], v[164:167], v[190:193], v[96:99]
	v_mfma_f32_16x16x32_f16 v[84:87], v[156:159], v[198:201], v[84:87]
	v_mfma_f32_16x16x32_f16 v[80:83], v[164:167], v[198:201], v[80:83]
	s_barrier
	s_add_i32 s52, 0, 0x1c000
	s_add_i32 s34, s97, s78
	v_add_u32_e32 v169, s52, v147
	v_lshl_add_u64 v[218:219], v[218:219], 0, s[8:9]
	s_mov_b32 m0, s34
	ds_read_b128 v[202:205], v169
	ds_read_b128 v[206:209], v169 offset:1024
	ds_read_b128 v[210:213], v169 offset:2048
	ds_read_b128 v[214:217], v169 offset:3072
	global_load_lds_dwordx4 v[218:219], off
	v_lshl_add_u64 v[218:219], v[220:221], 0, s[8:9]
	s_add_i32 m0, s34, 0x2000
	s_nop 0
	global_load_lds_dwordx4 v[218:219], off
	s_barrier
	s_waitcnt lgkmcnt(0)
	s_waitcnt lgkmcnt(0)
	v_mfma_f32_16x16x32_f16 v[108:111], v[202:205], v[170:173], v[108:111]
	v_mfma_f32_16x16x32_f16 v[104:107], v[210:213], v[170:173], v[104:107]
	v_mfma_f32_16x16x32_f16 v[92:95], v[202:205], v[178:181], v[92:95]
	v_mfma_f32_16x16x32_f16 v[88:91], v[210:213], v[178:181], v[88:91]
	v_mfma_f32_16x16x32_f16 v[76:79], v[202:205], v[186:189], v[76:79]
	v_mfma_f32_16x16x32_f16 v[72:75], v[210:213], v[186:189], v[72:75]
	v_mfma_f32_16x16x32_f16 v[68:71], v[202:205], v[194:197], v[68:71]
	v_mfma_f32_16x16x32_f16 v[64:67], v[210:213], v[194:197], v[64:67]
	v_mfma_f32_16x16x32_f16 v[108:111], v[206:209], v[174:177], v[108:111]
	v_mfma_f32_16x16x32_f16 v[104:107], v[214:217], v[174:177], v[104:107]
	v_mfma_f32_16x16x32_f16 v[92:95], v[206:209], v[182:185], v[92:95]
	v_mfma_f32_16x16x32_f16 v[88:91], v[214:217], v[182:185], v[88:91]
	v_mfma_f32_16x16x32_f16 v[76:79], v[206:209], v[190:193], v[76:79]
	v_mfma_f32_16x16x32_f16 v[72:75], v[214:217], v[190:193], v[72:75]
	v_mfma_f32_16x16x32_f16 v[68:71], v[206:209], v[198:201], v[68:71]
	v_mfma_f32_16x16x32_f16 v[64:67], v[214:217], v[198:201], v[64:67]
	s_mov_b32 m0, s85
	v_lshl_add_u64 v[218:219], v[222:223], 0, s[8:9]
	s_barrier
	ds_read_b128 v[170:173], v150 offset:49152
	ds_read_b128 v[174:177], v150 offset:50176
	ds_read_b128 v[178:181], v150 offset:51200
	ds_read_b128 v[182:185], v150 offset:52224
	ds_read_b128 v[186:189], v150 offset:53248
	ds_read_b128 v[190:193], v150 offset:54272
	ds_read_b128 v[194:197], v150 offset:55296
	ds_read_b128 v[198:201], v150 offset:56320
	global_load_lds_dwordx4 v[218:219], off
	v_lshl_add_u64 v[218:219], v[224:225], 0, s[8:9]
	s_mov_b32 m0, s86
	s_nop 0
	global_load_lds_dwordx4 v[218:219], off
	s_barrier
; #define PG8_STAGE(bufoff, gbase, voff) do { _Pragma("unroll") for (int _i = 0; _i < 2; ++_i) \
;         __builtin_amdgcn_global_load_lds((const unsigned*)((const char*)(gbase) + (voff)[_i]), (LAS unsigned*)(lds + (bufoff) + ldsw + _i * 8192), 16, 0, 0); } while (0)
; #define PG8_MMA(ai, bj, At, Bt) do { __builtin_amdgcn_s_setprio(1); _Pragma("unroll") for (int m = 0; m < 4; ++m) _Pragma("unroll") for (int n = 0; n < 2; ++n) _Pragma("unroll") for (int k = 0; k < 2; ++k) \
;         acc[ai][bj][m][n] = __builtin_amdgcn_mfma_f32_16x16x32_f16(Bt[n][k], At[m][k], acc[ai][bj][m][n], 0, 0, 0); __builtin_amdgcn_s_setprio(0); } while (0)
; #define PG8_WAIT_V(n) asm volatile("s_waitcnt vmcnt(" #n ")" ::: "memory")
; #define PG8_WAIT_L(n) asm volatile("s_waitcnt lgkmcnt(" #n ")" ::: "memory")
; #define PG8_BAR __builtin_amdgcn_s_barrier()
; #define PG8_SCHED __builtin_amdgcn_sched_barrier(0)
; template <class Epi>
; __device__ __forceinline__ void gemm_phase(LAS unsigned char* lds, const Gemm g, const StaticOrder& S, const Epi& E) {
;     ...
;             PG8_BAR; PG8_WAIT_L(0); PG8_MMA(1, 0, At, B0); PG8_BAR; PG8_SCHED;
;             PG8_STAGE(PG8_SB(1, 1), b3 + hstep, voffB);
;             PG8_WAIT_V(6); PG8_BAR; PG8_MMA(1, 1, At, B1); PG8_BAR;
	s_waitcnt lgkmcnt(0)
	s_waitcnt lgkmcnt(0)
	v_mfma_f32_16x16x32_f16 v[60:63], v[152:155], v[170:173], v[60:63]
	v_mfma_f32_16x16x32_f16 v[56:59], v[160:163], v[170:173], v[56:59]
	v_mfma_f32_16x16x32_f16 v[52:55], v[152:155], v[178:181], v[52:55]
	v_mfma_f32_16x16x32_f16 v[48:51], v[160:163], v[178:181], v[48:51]
	v_mfma_f32_16x16x32_f16 v[36:39], v[152:155], v[186:189], v[36:39]
	v_mfma_f32_16x16x32_f16 v[32:35], v[160:163], v[186:189], v[32:35]
	v_mfma_f32_16x16x32_f16 v[20:23], v[152:155], v[194:197], v[20:23]
	v_mfma_f32_16x16x32_f16 v[16:19], v[160:163], v[194:197], v[16:19]
	v_mfma_f32_16x16x32_f16 v[60:63], v[156:159], v[174:177], v[60:63]
	v_mfma_f32_16x16x32_f16 v[56:59], v[164:167], v[174:177], v[56:59]
	v_mfma_f32_16x16x32_f16 v[52:55], v[156:159], v[182:185], v[52:55]
	v_mfma_f32_16x16x32_f16 v[48:51], v[164:167], v[182:185], v[48:51]
	v_mfma_f32_16x16x32_f16 v[36:39], v[156:159], v[190:193], v[36:39]
	v_mfma_f32_16x16x32_f16 v[32:35], v[164:167], v[190:193], v[32:35]
	v_mfma_f32_16x16x32_f16 v[20:23], v[156:159], v[198:201], v[20:23]
	v_mfma_f32_16x16x32_f16 v[16:19], v[164:167], v[198:201], v[16:19]
	s_barrier
	s_add_u32 s34, s48, 0x80080
	s_addc_u32 s35, s49, 0
	s_add_i32 s48, s52, s78
	v_lshl_add_u64 v[152:153], s[34:35], 0, v[132:133]
	s_mov_b32 m0, s48
	s_nop 0
	global_load_lds_dwordx4 v[152:153], off
	v_lshl_add_u64 v[152:153], s[34:35], 0, v[136:137]
	s_add_i32 m0, s48, 0x2000
	s_nop 0
	global_load_lds_dwordx4 v[152:153], off
	s_waitcnt vmcnt(6)
	s_barrier
	v_mfma_f32_16x16x32_f16 v[44:47], v[202:205], v[170:173], v[44:47]
	v_mfma_f32_16x16x32_f16 v[40:43], v[210:213], v[170:173], v[40:43]
	v_mfma_f32_16x16x32_f16 v[28:31], v[202:205], v[178:181], v[28:31]
	v_mfma_f32_16x16x32_f16 v[24:27], v[210:213], v[178:181], v[24:27]
	v_mfma_f32_16x16x32_f16 v[12:15], v[202:205], v[186:189], v[12:15]
	v_mfma_f32_16x16x32_f16 v[8:11], v[210:213], v[186:189], v[8:11]
	v_mfma_f32_16x16x32_f16 v[4:7], v[202:205], v[194:197], v[4:7]
	v_mfma_f32_16x16x32_f16 v[0:3], v[210:213], v[194:197], v[0:3]
	v_mfma_f32_16x16x32_f16 v[44:47], v[206:209], v[174:177], v[44:47]
	v_mfma_f32_16x16x32_f16 v[40:43], v[214:217], v[174:177], v[40:43]
	v_mfma_f32_16x16x32_f16 v[28:31], v[206:209], v[182:185], v[28:31]
	v_mfma_f32_16x16x32_f16 v[24:27], v[214:217], v[182:185], v[24:27]
	v_mfma_f32_16x16x32_f16 v[12:15], v[206:209], v[190:193], v[12:15]
	v_mfma_f32_16x16x32_f16 v[8:11], v[214:217], v[190:193], v[8:11]
	v_mfma_f32_16x16x32_f16 v[4:7], v[206:209], v[198:201], v[4:7]
	v_mfma_f32_16x16x32_f16 v[0:3], v[214:217], v[198:201], v[0:3]
	s_add_i32 s15, s15, 2
	s_add_u32 s46, s46, 0x100
	s_addc_u32 s47, s47, 0
	s_add_u32 s96, s96, 0x100
	s_addc_u32 s14, s14, 0
	s_cmp_gt_u32 s15, 29
	s_barrier
	s_cbranch_scc0 .LBB0_356
; #define PG8_WAIT_V(n) asm volatile("s_waitcnt vmcnt(" #n ")" ::: "memory")
; #define PG8_BAR __builtin_amdgcn_s_barrier()
; template <class Epi>
; __device__ __forceinline__ void gemm_phase(LAS unsigned char* lds, const Gemm g, const StaticOrder& S, const Epi& E) {
;     ...
;         cur = nxt; cA = nA; cB = nB; ++ui;
;     }
;     PG8_WAIT_V(0);
;     if (wr == 0) PG8_BAR;
;     PG8_BAR;
;     __device__ __forceinline__ void operator()(const f32x4 (&acc)[2][2][4][2], const pg8::Unit& u, int wr, int wc, int fr, int fq) const {
;         const int row0 = u.pm * 256 + wr * 64 + fr, col0 = u.pn * 256 + wc * 32 + 8 * fq;
; #pragma unroll
;         for (int ai = 0; ai < 2; ++ai)
; #pragma unroll
;             for (int m = 0; m < 4; ++m) { const size_t r = (size_t)(row0 + ai * 128 + m * 16);
; #pragma unroll
;                 for (int bj = 0; bj < 2; ++bj) { const f32x4 v0 = acc[ai][bj][m][0], v1 = acc[ai][bj][m][1]; h16x8 o;
; #pragma unroll
;                     for (int e = 0; e < 4; ++e) { o[e] = (h16)v0[e]; o[4 + e] = (h16)v1[e]; }
;                     *(h16x8*)(O1 + r * 1024 + col0 + bj * 128) = o; } }
	v_lshl_add_u32 v152, s22, 8, v146
	v_lshl_or_b32 v154, s93, 8, v148
	v_ashrrev_i32_e32 v153, 31, v152
	v_ashrrev_i32_e32 v155, 31, v154
	v_lshlrev_b64 v[156:157], 11, v[152:153]
	v_cvt_pk_f16_f32 v123, v122, v123
	v_cvt_pk_f16_f32 v122, v120, v121
	v_cvt_pk_f16_f32 v121, v126, v127
	v_cvt_pk_f16_f32 v120, v124, v125
	v_lshl_add_u64 v[124:125], s[6:7], 0, v[156:157]
	v_lshlrev_b64 v[126:127], 1, v[154:155]
	v_lshl_add_u64 v[124:125], v[124:125], 0, v[126:127]
	v_cvt_pk_f16_f32 v107, v106, v107
	v_cvt_pk_f16_f32 v106, v104, v105
	v_cvt_pk_f16_f32 v105, v110, v111
	v_cvt_pk_f16_f32 v104, v108, v109
	global_store_dwordx4 v[124:125], v[104:107], off offset:256
	v_cvt_pk_f16_f32 v91, v90, v91
	v_cvt_pk_f16_f32 v90, v88, v89
	v_or_b32_e32 v104, 16, v152
	v_ashrrev_i32_e32 v105, 31, v104
	v_lshlrev_b64 v[108:109], 11, v[104:105]
	v_lshl_add_u64 v[108:109], s[6:7], 0, v[108:109]
	v_lshl_add_u64 v[108:109], v[108:109], 0, v[126:127]
	v_cvt_pk_f16_f32 v89, v94, v95
	v_cvt_pk_f16_f32 v88, v92, v93
	global_store_dwordx4 v[108:109], v[88:91], off offset:256
	v_cvt_pk_f16_f32 v59, v58, v59
	v_cvt_pk_f16_f32 v58, v56, v57
	v_or_b32_e32 v88, 32, v152
	v_ashrrev_i32_e32 v89, 31, v88
	v_cvt_pk_f16_f32 v57, v62, v63
	v_add_co_u32_e32 v62, vcc, s90, v124
	v_lshlrev_b64 v[92:93], 11, v[88:89]
	s_nop 0
	v_addc_co_u32_e32 v63, vcc, 0, v125, vcc
	v_lshl_add_u64 v[92:93], s[6:7], 0, v[92:93]
	v_cvt_pk_f16_f32 v43, v42, v43
	v_cvt_pk_f16_f32 v42, v40, v41
	v_cvt_pk_f16_f32 v41, v46, v47
	v_add_co_u32_e32 v46, vcc, s91, v124
	v_lshl_add_u64 v[92:93], v[92:93], 0, v[126:127]
	v_cvt_pk_f16_f32 v75, v74, v75
	v_cvt_pk_f16_f32 v74, v72, v73
	v_cvt_pk_f16_f32 v73, v78, v79
	v_cvt_pk_f16_f32 v72, v76, v77
	v_addc_co_u32_e32 v47, vcc, 0, v125, vcc
	global_store_dwordx4 v[92:93], v[72:75], off offset:256
	v_cvt_pk_f16_f32 v27, v26, v27
	v_cvt_pk_f16_f32 v26, v24, v25
	v_or_b32_e32 v72, 48, v152
	v_cvt_pk_f16_f32 v25, v30, v31
	v_add_co_u32_e32 v30, vcc, s92, v124
	v_ashrrev_i32_e32 v73, 31, v72
	s_nop 0
	v_addc_co_u32_e32 v31, vcc, 0, v125, vcc
	v_lshlrev_b64 v[76:77], 11, v[72:73]
	v_cvt_pk_f16_f32 v11, v10, v11
	v_cvt_pk_f16_f32 v10, v8, v9
	v_cvt_pk_f16_f32 v9, v14, v15
	v_add_co_u32_e32 v14, vcc, 0x58000, v124
	v_lshl_add_u64 v[76:77], s[6:7], 0, v[76:77]
	v_cvt_pk_f16_f32 v56, v60, v61
	v_lshl_add_u64 v[60:61], v[124:125], 0, s[10:11]
	v_cvt_pk_f16_f32 v40, v44, v45
	v_lshl_add_u64 v[44:45], v[124:125], 0, s[12:13]
	v_cvt_pk_f16_f32 v24, v28, v29
	v_lshl_add_u64 v[28:29], v[124:125], 0, s[18:19]
	v_cvt_pk_f16_f32 v8, v12, v13
	v_addc_co_u32_e32 v15, vcc, 0, v125, vcc
	v_cvt_pk_f16_f32 v107, v114, v115
	v_cvt_pk_f16_f32 v106, v112, v113
	v_cvt_pk_f16_f32 v105, v118, v119
	v_cvt_pk_f16_f32 v104, v116, v117
	v_cvt_pk_f16_f32 v91, v98, v99
	v_cvt_pk_f16_f32 v90, v96, v97
	v_cvt_pk_f16_f32 v89, v102, v103
	v_cvt_pk_f16_f32 v88, v100, v101
	v_cvt_pk_f16_f32 v75, v82, v83
	v_cvt_pk_f16_f32 v74, v80, v81
	v_cvt_pk_f16_f32 v73, v86, v87
	v_cvt_pk_f16_f32 v72, v84, v85
	v_lshl_add_u64 v[76:77], v[76:77], 0, v[126:127]
	v_cvt_pk_f16_f32 v67, v66, v67
	v_cvt_pk_f16_f32 v66, v64, v65
	v_cvt_pk_f16_f32 v65, v70, v71
	v_cvt_pk_f16_f32 v64, v68, v69
	global_store_dwordx4 v[60:61], v[40:43], off offset:256
	global_store_dwordx4 v[44:45], v[24:27], off offset:256
	global_store_dwordx4 v[28:29], v[8:11], off offset:256
	v_cvt_pk_f16_f32 v43, v50, v51
	v_cvt_pk_f16_f32 v42, v48, v49
	v_cvt_pk_f16_f32 v41, v54, v55
	v_cvt_pk_f16_f32 v40, v52, v53
	v_cvt_pk_f16_f32 v27, v34, v35
	v_cvt_pk_f16_f32 v26, v32, v33
	v_cvt_pk_f16_f32 v25, v38, v39
	v_cvt_pk_f16_f32 v24, v36, v37
	v_cvt_pk_f16_f32 v11, v18, v19
	v_cvt_pk_f16_f32 v10, v16, v17
	v_cvt_pk_f16_f32 v9, v22, v23
	v_cvt_pk_f16_f32 v8, v20, v21
	v_lshl_add_u64 v[12:13], v[124:125], 0, s[20:21]
	v_cvt_pk_f16_f32 v3, v2, v3
	v_cvt_pk_f16_f32 v2, v0, v1
	v_cvt_pk_f16_f32 v1, v6, v7
	v_cvt_pk_f16_f32 v0, v4, v5
	s_and_b64 vcc, exec, s[0:1]
	s_mov_b32 s93, s24
	s_mov_b32 s22, s26
	s_mov_b64 s[48:49], s[30:31]
	s_mov_b64 s[46:47], s[28:29]
	global_store_dwordx4 v[124:125], v[120:123], off
	global_store_dwordx4 v[108:109], v[104:107], off
	global_store_dwordx4 v[92:93], v[88:91], off
	global_store_dwordx4 v[76:77], v[72:75], off
	global_store_dwordx4 v[76:77], v[64:67], off offset:256
	global_store_dwordx4 v[62:63], v[56:59], off
	global_store_dwordx4 v[46:47], v[40:43], off
	global_store_dwordx4 v[30:31], v[24:27], off
	global_store_dwordx4 v[14:15], v[8:11], off
	global_store_dwordx4 v[12:13], v[0:3], off offset:256
	s_cbranch_vccz .LBB0_349
	s_waitcnt vmcnt(0)
	s_cmpk_gt_u32 s33, 0xff
	s_cbranch_scc1 .LBB0_360
	s_barrier

; #define PG8_STAGE(bufoff, gbase, voff) do { _Pragma("unroll") for (int _i = 0; _i < 2; ++_i) \
;         __builtin_amdgcn_global_load_lds((const unsigned*)((const char*)(gbase) + (voff)[_i]), (LAS unsigned*)(lds + (bufoff) + ldsw + _i * 8192), 16, 0, 0); } while (0)
; #define PG8_BAR __builtin_amdgcn_s_barrier()
; template <class Epi>
; __device__ __forceinline__ void gemm_phase(LAS unsigned char* lds, const Gemm g, const StaticOrder& S, const Epi& E) {
;     const int tid = threadIdx.x, wid = __builtin_amdgcn_readfirstlane(tid >> 6), lane = tid & 63, wr = wid >> 2, wc = wid & 3, fr = lane & 15, fq = lane >> 4;
;     const int K = g.K, nt = K / BK;
;     unsigned voffA[2], voffB[2];
; #pragma unroll
;     for (int i = 0; i < 2; ++i) { int R, C; stage_rc(tid * 16 + i * 8192, R, C); const int Rb = Epi::PERM ? ((R & ~31) + perm32(R & 31)) : R; voffA[i] = (unsigned)(R * K + C) * 2u; voffB[i] = (unsigned)(Rb * K + C) * 2u; }
;     const size_t kstep = (size_t)(BK * 2);
;     const size_t hstep = (size_t)HALF * K * 2;
;     const size_t tstep = 2 * hstep;
;     const unsigned ldsw = (unsigned)wid * 1024u;
;     const int aoff = lds_byte(wr * 64 + fr, fq * 8), boff = lds_byte(wc * 32 + fr, fq * 8);
;     ...
;     Unit cur, nxt; int ui = 0;
;     if (!S.next(0, cur)) return;
;     f32x4 acc[2][2][4][2];
; #pragma unroll
;     for (int a = 0; a < 2; ++a)
; #pragma unroll
;         for (int b = 0; b < 2; ++b)
; #pragma unroll
;             for (int m = 0; m < 4; ++m)
; #pragma unroll
;                 for (int n = 0; n < 2; ++n) acc[a][b][m][n] = (f32x4){0.f, 0.f, 0.f, 0.f};
;     h16x8 At[4][2], B0[2][2], B1[2][2];
;     const char* cA = (const char*)g.A + (size_t)cur.pm * tstep; const char* cB = (const char*)g.Bt + (size_t)cur.pn * tstep;
;     PG8_STAGE(PG8_SB(0, 0), cB, voffB); PG8_STAGE(PG8_SA(0, 0), cA, voffA); PG8_STAGE(PG8_SB(0, 1), cB + hstep, voffB); PG8_STAGE(PG8_SA(0, 1), cA + hstep, voffA);
;     if (wr == 1) PG8_BAR;
.LBB0_477:
	s_andn2_b64 vcc, exec, s[0:1]
	s_cbranch_vccnz .LBB0_521
	v_lshrrev_b32_e32 v2, 1, v130
	v_and_b32_e32 v11, 24, v2
	v_lshrrev_b32_e32 v2, 5, v130
	v_and_b32_e32 v2, 4, v2
	v_bfe_u32 v3, v130, 2, 2
	v_lshlrev_b32_e32 v0, 4, v130
	v_and_b32_e32 v1, 32, v130
	v_bfe_u32 v10, v130, 2, 4
	v_or3_b32 v2, v2, v3, v11
	v_lshrrev_b32_e32 v3, 3, v130
	s_movk_i32 s0, 0x70
	v_bitop3_b32 v8, v0, v1, 48 bitop3:0x6c
	v_and_b32_e32 v9, 64, v130
	v_and_or_b32 v4, v3, s0, v10
	s_movk_i32 s0, 0x60
	v_add_u32_e32 v12, 0x2000, v0
	s_add_u32 s82, s70, 0x1200000
	v_or_b32_e32 v1, v8, v9
	v_and_or_b32 v3, v3, s0, v2
	v_lshrrev_b32_e32 v0, 7, v12
	s_movk_i32 s0, 0xf0
	s_addc_u32 s83, s71, 0
	v_lshl_or_b32 v132, v3, 11, v1
	v_and_or_b32 v3, v0, s0, v10
	s_movk_i32 s0, 0xe0
	s_lshr_b32 s1, s33, 6
	s_waitcnt lgkmcnt(0)
	s_ashr_i32 s57, s56, 31
	s_ashr_i32 s55, s54, 31
	v_and_or_b32 v0, v0, s0, v2
	s_lshr_b32 s0, s33, 8
	s_lshl_b32 s84, s1, 10
	s_lshl_b64 s[6:7], s[56:57], 19
	s_lshl_b64 s[8:9], s[54:55], 19
	s_add_u32 s78, s82, s8
	s_addc_u32 s79, s83, s9
	s_add_i32 s85, s84, 0
	s_add_i32 m0, s85, 0x10000
	v_lshl_or_b32 v136, v0, 11, v1
	global_load_lds_dwordx4 v132, s[78:79]
	s_add_i32 m0, s85, 0x12000
	s_add_u32 s76, s68, s6
	v_lshl_or_b32 v128, v4, 11, v1
	global_load_lds_dwordx4 v136, s[78:79]
	s_addc_u32 s77, s69, s7
	s_mov_b32 m0, s85
	s_add_i32 s86, s85, 0x2000
	v_lshl_or_b32 v134, v3, 11, v1
	global_load_lds_dwordx4 v128, s[76:77]
	s_mov_b32 m0, s86
	s_add_u32 s6, s78, 0x40000
	global_load_lds_dwordx4 v134, s[76:77]
	s_addc_u32 s7, s79, 0
	s_add_i32 m0, s85, 0x14000
	v_mov_b32_e32 v139, 0
	global_load_lds_dwordx4 v132, s[6:7]
	s_add_i32 m0, s85, 0x16000
	v_mov_b32_e32 v133, v139
	global_load_lds_dwordx4 v136, s[6:7]
	s_add_u32 s6, s76, 0x40000
	s_addc_u32 s7, s77, 0
	s_add_i32 s87, s85, 0x4000
	s_mov_b32 m0, s87
	s_add_i32 s88, s85, 0x6000
	global_load_lds_dwordx4 v128, s[6:7]
	s_mov_b32 m0, s88
	v_mov_b32_e32 v137, v139
	global_load_lds_dwordx4 v134, s[6:7]
	v_mov_b32_e32 v129, v139
	v_mov_b32_e32 v135, v139
	s_mov_b32 s89, 0
	v_lshl_add_u64 v[6:7], s[78:79], 0, v[132:133]
	v_lshl_add_u64 v[4:5], s[78:79], 0, v[136:137]
	v_lshl_add_u64 v[2:3], s[76:77], 0, v[128:129]
	s_cmp_lg_u32 s0, 1
	v_lshl_add_u64 v[0:1], s[76:77], 0, v[134:135]
	s_cbranch_scc1 .LBB0_480
	s_barrier
	s_setprio 1

; #define PG8_STAGE(bufoff, gbase, voff) do { _Pragma("unroll") for (int _i = 0; _i < 2; ++_i) \
;         __builtin_amdgcn_global_load_lds((const unsigned*)((const char*)(gbase) + (voff)[_i]), (LAS unsigned*)(lds + (bufoff) + ldsw + _i * 8192), 16, 0, 0); } while (0)
; #define PG8_LDA(dst, b, h) do { _Pragma("unroll") for (int m = 0; m < 4; ++m) _Pragma("unroll") for (int k = 0; k < 2; ++k) dst[m][k] = *(const LAS h16x8*)(lds + PG8_SA(b, h) + aoff + m * 2048 + k * 1024); } while (0)
; #define PG8_LDB(dst, b, h) do { _Pragma("unroll") for (int n = 0; n < 2; ++n) _Pragma("unroll") for (int k = 0; k < 2; ++k) dst[n][k] = *(const LAS h16x8*)(lds + PG8_SB(b, h) + boff + n * 2048 + k * 1024); } while (0)
; #define PG8_MMA(ai, bj, At, Bt) do { __builtin_amdgcn_s_setprio(1); _Pragma("unroll") for (int m = 0; m < 4; ++m) _Pragma("unroll") for (int n = 0; n < 2; ++n) _Pragma("unroll") for (int k = 0; k < 2; ++k) \
;         acc[ai][bj][m][n] = __builtin_amdgcn_mfma_f32_16x16x32_f16(Bt[n][k], At[m][k], acc[ai][bj][m][n], 0, 0, 0); __builtin_amdgcn_s_setprio(0); } while (0)
; #define PG8_WAIT_L(n) asm volatile("s_waitcnt lgkmcnt(" #n ")" ::: "memory")
; #define PG8_BAR __builtin_amdgcn_s_barrier()
; #define PG8_SCHED __builtin_amdgcn_sched_barrier(0)
; template <class Epi>
; __device__ __forceinline__ void gemm_phase(LAS unsigned char* lds, const Gemm g, const StaticOrder& S, const Epi& E) {
;     ...
;             PG8_LDB(B0, 0, 0); PG8_SCHED; PG8_LDA(At, 0, 0); PG8_STAGE(PG8_SA(1, 1), a1 + hstep, voffA);
;             PG8_WAIT_L(8); PG8_BAR; PG8_WAIT_L(0); PG8_MMA(0, 0, At, B0); PG8_BAR; PG8_SCHED;
;             PG8_LDB(B1, 0, 1); PG8_STAGE(PG8_SB(0, 0), b2, voffB);
;             PG8_BAR; PG8_WAIT_L(0); PG8_MMA(0, 1, At, B1); PG8_BAR;
;             PG8_LDA(At, 0, 1); PG8_STAGE(PG8_SA(0, 0), a2, voffA);
;             PG8_BAR; PG8_WAIT_L(0); PG8_MMA(1, 0, At, B0); PG8_BAR; PG8_SCHED;
;             PG8_STAGE(PG8_SB(0, 1), b2 + hstep, voffB);
.LBB0_485:
	ds_read_b128 v[148:151], v165
	ds_read_b128 v[152:155], v165 offset:1024
	ds_read_b128 v[156:159], v165 offset:2048
	ds_read_b128 v[170:173], v165 offset:3072
	s_add_u32 s34, s76, 0xfffc0080
	s_addc_u32 s35, s77, -1
	s_cmp_eq_u32 s15, 12
	s_cselect_b32 s81, s47, s35
	s_cselect_b32 s80, s55, s34
	s_cselect_b32 s79, s31, s14
	s_cselect_b32 s78, s57, vcc_lo
	v_lshl_add_u64 v[160:161], s[76:77], 0, v[140:141]
	s_add_i32 m0, s85, 0xc000
	ds_read_b128 v[174:177], v166
	ds_read_b128 v[178:181], v166 offset:1024
	ds_read_b128 v[182:185], v166 offset:2048
	ds_read_b128 v[186:189], v166 offset:3072
	ds_read_b128 v[190:193], v166 offset:4096
	ds_read_b128 v[194:197], v166 offset:5120
	ds_read_b128 v[198:201], v166 offset:6144
	ds_read_b128 v[202:205], v166 offset:7168
	global_load_lds_dwordx4 v[160:161], off
	v_lshl_add_u64 v[160:161], s[76:77], 0, v[142:143]
	s_add_i32 m0, s85, 0xe000
	s_nop 0
	global_load_lds_dwordx4 v[160:161], off
	s_waitcnt lgkmcnt(8)
	s_barrier
	s_waitcnt lgkmcnt(0)
	s_waitcnt lgkmcnt(0)
	v_mfma_f32_16x16x32_f16 v[124:127], v[148:151], v[174:177], v[124:127]
	v_mfma_f32_16x16x32_f16 v[120:123], v[156:159], v[174:177], v[120:123]
	v_mfma_f32_16x16x32_f16 v[116:119], v[148:151], v[182:185], v[116:119]
	v_mfma_f32_16x16x32_f16 v[112:115], v[156:159], v[182:185], v[112:115]
	v_mfma_f32_16x16x32_f16 v[108:111], v[148:151], v[190:193], v[108:111]
	v_mfma_f32_16x16x32_f16 v[104:107], v[156:159], v[190:193], v[104:107]
	v_mfma_f32_16x16x32_f16 v[100:103], v[148:151], v[198:201], v[100:103]
	v_mfma_f32_16x16x32_f16 v[96:99], v[156:159], v[198:201], v[96:99]
	v_mfma_f32_16x16x32_f16 v[124:127], v[152:155], v[178:181], v[124:127]
	v_mfma_f32_16x16x32_f16 v[120:123], v[170:173], v[178:181], v[120:123]
	v_mfma_f32_16x16x32_f16 v[116:119], v[152:155], v[186:189], v[116:119]
	v_mfma_f32_16x16x32_f16 v[112:115], v[170:173], v[186:189], v[112:115]
	v_mfma_f32_16x16x32_f16 v[108:111], v[152:155], v[194:197], v[108:111]
	v_mfma_f32_16x16x32_f16 v[104:107], v[170:173], v[194:197], v[104:107]
	v_mfma_f32_16x16x32_f16 v[100:103], v[152:155], v[202:205], v[100:103]
	v_mfma_f32_16x16x32_f16 v[96:99], v[170:173], v[202:205], v[96:99]
	s_barrier
	s_add_i32 s34, s95, s84
	v_lshl_add_u64 v[160:161], s[78:79], 0, v[132:133]
	s_mov_b32 m0, s34
	ds_read_b128 v[206:209], v167
	ds_read_b128 v[210:213], v167 offset:1024
	ds_read_b128 v[214:217], v167 offset:2048
	ds_read_b128 v[218:221], v167 offset:3072
	global_load_lds_dwordx4 v[160:161], off
	v_lshl_add_u64 v[222:223], s[78:79], 0, v[136:137]
	s_add_i32 m0, s34, 0x2000
	s_nop 0
	global_load_lds_dwordx4 v[222:223], off
	s_barrier
	s_waitcnt lgkmcnt(0)
	s_waitcnt lgkmcnt(0)
	v_mfma_f32_16x16x32_f16 v[60:63], v[206:209], v[174:177], v[60:63]
	v_mfma_f32_16x16x32_f16 v[56:59], v[214:217], v[174:177], v[56:59]
	v_mfma_f32_16x16x32_f16 v[52:55], v[206:209], v[182:185], v[52:55]
	v_mfma_f32_16x16x32_f16 v[48:51], v[214:217], v[182:185], v[48:51]
	v_mfma_f32_16x16x32_f16 v[44:47], v[206:209], v[190:193], v[44:47]
	v_mfma_f32_16x16x32_f16 v[40:43], v[214:217], v[190:193], v[40:43]
	v_mfma_f32_16x16x32_f16 v[36:39], v[206:209], v[198:201], v[36:39]
	v_mfma_f32_16x16x32_f16 v[32:35], v[214:217], v[198:201], v[32:35]
	v_mfma_f32_16x16x32_f16 v[60:63], v[210:213], v[178:181], v[60:63]
	v_mfma_f32_16x16x32_f16 v[56:59], v[218:221], v[178:181], v[56:59]
	v_mfma_f32_16x16x32_f16 v[52:55], v[210:213], v[186:189], v[52:55]
	v_mfma_f32_16x16x32_f16 v[48:51], v[218:221], v[186:189], v[48:51]
	v_mfma_f32_16x16x32_f16 v[44:47], v[210:213], v[194:197], v[44:47]
	v_mfma_f32_16x16x32_f16 v[40:43], v[218:221], v[194:197], v[40:43]
	v_mfma_f32_16x16x32_f16 v[36:39], v[210:213], v[202:205], v[36:39]
	v_mfma_f32_16x16x32_f16 v[32:35], v[218:221], v[202:205], v[32:35]
	s_mov_b32 m0, s85
	v_lshl_add_u64 v[224:225], s[80:81], 0, v[128:129]
	s_barrier
	ds_read_b128 v[174:177], v166 offset:16384
	ds_read_b128 v[178:181], v166 offset:17408
	ds_read_b128 v[182:185], v166 offset:18432
	ds_read_b128 v[186:189], v166 offset:19456
	ds_read_b128 v[190:193], v166 offset:20480
	ds_read_b128 v[194:197], v166 offset:21504
	ds_read_b128 v[198:201], v166 offset:22528
	ds_read_b128 v[202:205], v166 offset:23552
	global_load_lds_dwordx4 v[224:225], off
	v_lshl_add_u64 v[226:227], s[80:81], 0, v[134:135]
	s_mov_b32 m0, s86
	s_nop 0
	global_load_lds_dwordx4 v[226:227], off
	s_barrier
	s_waitcnt lgkmcnt(0)
	s_waitcnt lgkmcnt(0)
	v_mfma_f32_16x16x32_f16 v[92:95], v[148:151], v[174:177], v[92:95]
	v_mfma_f32_16x16x32_f16 v[88:91], v[156:159], v[174:177], v[88:91]
	v_mfma_f32_16x16x32_f16 v[84:87], v[148:151], v[182:185], v[84:87]
	v_mfma_f32_16x16x32_f16 v[80:83], v[156:159], v[182:185], v[80:83]
	v_mfma_f32_16x16x32_f16 v[76:79], v[148:151], v[190:193], v[76:79]
	v_mfma_f32_16x16x32_f16 v[72:75], v[156:159], v[190:193], v[72:75]
	v_mfma_f32_16x16x32_f16 v[68:71], v[148:151], v[198:201], v[68:71]
	v_mfma_f32_16x16x32_f16 v[64:67], v[156:159], v[198:201], v[64:67]
	v_mfma_f32_16x16x32_f16 v[92:95], v[152:155], v[178:181], v[92:95]
	v_mfma_f32_16x16x32_f16 v[88:91], v[170:173], v[178:181], v[88:91]
	v_mfma_f32_16x16x32_f16 v[84:87], v[152:155], v[186:189], v[84:87]
	v_mfma_f32_16x16x32_f16 v[80:83], v[170:173], v[186:189], v[80:83]
	v_mfma_f32_16x16x32_f16 v[76:79], v[152:155], v[194:197], v[76:79]
	v_mfma_f32_16x16x32_f16 v[72:75], v[170:173], v[194:197], v[72:75]
	v_mfma_f32_16x16x32_f16 v[68:71], v[152:155], v[202:205], v[68:71]
	v_mfma_f32_16x16x32_f16 v[64:67], v[170:173], v[202:205], v[64:67]
	s_barrier
; #define PG8_STAGE(bufoff, gbase, voff) do { _Pragma("unroll") for (int _i = 0; _i < 2; ++_i) \
;         __builtin_amdgcn_global_load_lds((const unsigned*)((const char*)(gbase) + (voff)[_i]), (LAS unsigned*)(lds + (bufoff) + ldsw + _i * 8192), 16, 0, 0); } while (0)
; #define PG8_LDA(dst, b, h) do { _Pragma("unroll") for (int m = 0; m < 4; ++m) _Pragma("unroll") for (int k = 0; k < 2; ++k) dst[m][k] = *(const LAS h16x8*)(lds + PG8_SA(b, h) + aoff + m * 2048 + k * 1024); } while (0)
; #define PG8_LDB(dst, b, h) do { _Pragma("unroll") for (int n = 0; n < 2; ++n) _Pragma("unroll") for (int k = 0; k < 2; ++k) dst[n][k] = *(const LAS h16x8*)(lds + PG8_SB(b, h) + boff + n * 2048 + k * 1024); } while (0)
; #define PG8_MMA(ai, bj, At, Bt) do { __builtin_amdgcn_s_setprio(1); _Pragma("unroll") for (int m = 0; m < 4; ++m) _Pragma("unroll") for (int n = 0; n < 2; ++n) _Pragma("unroll") for (int k = 0; k < 2; ++k) \
;         acc[ai][bj][m][n] = __builtin_amdgcn_mfma_f32_16x16x32_f16(Bt[n][k], At[m][k], acc[ai][bj][m][n], 0, 0, 0); __builtin_amdgcn_s_setprio(0); } while (0)
; #define PG8_WAIT_V(n) asm volatile("s_waitcnt vmcnt(" #n ")" ::: "memory")
; #define PG8_WAIT_L(n) asm volatile("s_waitcnt lgkmcnt(" #n ")" ::: "memory")
; #define PG8_BAR __builtin_amdgcn_s_barrier()
; #define PG8_SCHED __builtin_amdgcn_sched_barrier(0)
; template <class Epi>
; __device__ __forceinline__ void gemm_phase(LAS unsigned char* lds, const Gemm g, const StaticOrder& S, const Epi& E) {
;     ...
;             PG8_STAGE(PG8_SB(0, 1), b2 + hstep, voffB);
;             PG8_WAIT_V(6); PG8_BAR; PG8_MMA(1, 1, At, B1); PG8_BAR;
;             PG8_LDB(B0, 1, 0); PG8_SCHED; PG8_LDA(At, 1, 0); PG8_STAGE(PG8_SA(0, 1), a2 + hstep, voffA);
;             PG8_WAIT_L(8); PG8_BAR; PG8_WAIT_L(0); PG8_MMA(0, 0, At, B0); PG8_BAR; PG8_SCHED;
;             PG8_LDB(B1, 1, 1); PG8_STAGE(PG8_SB(1, 0), b3, voffB);
;             PG8_BAR; PG8_WAIT_L(0); PG8_MMA(0, 1, At, B1); PG8_BAR;
;             PG8_LDA(At, 1, 1); PG8_STAGE(PG8_SA(1, 0), a3, voffA);
;             PG8_BAR; PG8_WAIT_L(0); PG8_MMA(1, 0, At, B0); PG8_BAR; PG8_SCHED;
	s_add_u32 s34, s78, 0x40000
	s_addc_u32 s35, s79, 0
	s_add_i32 vcc_hi, s96, s84
	v_lshl_add_u64 v[148:149], s[34:35], 0, v[132:133]
	s_mov_b32 m0, vcc_hi
	s_nop 0
	global_load_lds_dwordx4 v[148:149], off
	v_lshl_add_u64 v[148:149], s[34:35], 0, v[136:137]
	s_add_i32 m0, vcc_hi, 0x2000
	s_nop 0
	global_load_lds_dwordx4 v[148:149], off
	s_waitcnt vmcnt(6)
	s_barrier
	v_mfma_f32_16x16x32_f16 v[28:31], v[206:209], v[174:177], v[28:31]
	v_mfma_f32_16x16x32_f16 v[24:27], v[214:217], v[174:177], v[24:27]
	v_mfma_f32_16x16x32_f16 v[20:23], v[206:209], v[182:185], v[20:23]
	v_mfma_f32_16x16x32_f16 v[16:19], v[214:217], v[182:185], v[16:19]
	v_mfma_f32_16x16x32_f16 v[12:15], v[206:209], v[190:193], v[12:15]
	v_mfma_f32_16x16x32_f16 v[8:11], v[214:217], v[190:193], v[8:11]
	v_mfma_f32_16x16x32_f16 v[4:7], v[206:209], v[198:201], v[4:7]
	v_mfma_f32_16x16x32_f16 v[0:3], v[214:217], v[198:201], v[0:3]
	v_mfma_f32_16x16x32_f16 v[28:31], v[210:213], v[178:181], v[28:31]
	v_mfma_f32_16x16x32_f16 v[24:27], v[218:221], v[178:181], v[24:27]
	v_mfma_f32_16x16x32_f16 v[20:23], v[210:213], v[186:189], v[20:23]
	v_mfma_f32_16x16x32_f16 v[16:19], v[218:221], v[186:189], v[16:19]
	v_mfma_f32_16x16x32_f16 v[12:15], v[210:213], v[194:197], v[12:15]
	v_mfma_f32_16x16x32_f16 v[8:11], v[218:221], v[194:197], v[8:11]
	v_mfma_f32_16x16x32_f16 v[4:7], v[210:213], v[202:205], v[4:7]
	v_mfma_f32_16x16x32_f16 v[0:3], v[218:221], v[202:205], v[0:3]
	s_add_i32 vcc_hi, 0, 0x18000
	v_add_u32_e32 v138, vcc_hi, v163
	s_barrier
	ds_read_b128 v[148:151], v138
	ds_read_b128 v[152:155], v138 offset:1024
	ds_read_b128 v[156:159], v138 offset:2048
	ds_read_b128 v[170:173], v138 offset:3072
	s_add_u32 s34, s80, 0x40000
	s_addc_u32 s35, s81, 0
	s_mov_b32 m0, s87
	v_lshl_add_u64 v[206:207], s[34:35], 0, v[128:129]
	ds_read_b128 v[174:177], v166 offset:32768
	ds_read_b128 v[178:181], v166 offset:33792
	ds_read_b128 v[182:185], v166 offset:34816
	ds_read_b128 v[186:189], v166 offset:35840
	ds_read_b128 v[190:193], v166 offset:36864
	ds_read_b128 v[194:197], v166 offset:37888
	ds_read_b128 v[198:201], v166 offset:38912
	ds_read_b128 v[202:205], v166 offset:39936
	global_load_lds_dwordx4 v[206:207], off
	v_lshl_add_u64 v[206:207], s[34:35], 0, v[134:135]
	s_mov_b32 m0, s88
	s_nop 0
	global_load_lds_dwordx4 v[206:207], off
	s_waitcnt lgkmcnt(8)
	s_barrier
	s_waitcnt lgkmcnt(0)
	s_waitcnt lgkmcnt(0)
	v_mfma_f32_16x16x32_f16 v[124:127], v[148:151], v[174:177], v[124:127]
	v_mfma_f32_16x16x32_f16 v[120:123], v[156:159], v[174:177], v[120:123]
	v_mfma_f32_16x16x32_f16 v[116:119], v[148:151], v[182:185], v[116:119]
	v_mfma_f32_16x16x32_f16 v[112:115], v[156:159], v[182:185], v[112:115]
	v_mfma_f32_16x16x32_f16 v[108:111], v[148:151], v[190:193], v[108:111]
	v_mfma_f32_16x16x32_f16 v[104:107], v[156:159], v[190:193], v[104:107]
	v_mfma_f32_16x16x32_f16 v[100:103], v[148:151], v[198:201], v[100:103]
	v_mfma_f32_16x16x32_f16 v[96:99], v[156:159], v[198:201], v[96:99]
	v_mfma_f32_16x16x32_f16 v[124:127], v[152:155], v[178:181], v[124:127]
	v_mfma_f32_16x16x32_f16 v[120:123], v[170:173], v[178:181], v[120:123]
	v_mfma_f32_16x16x32_f16 v[116:119], v[152:155], v[186:189], v[116:119]
	v_mfma_f32_16x16x32_f16 v[112:115], v[170:173], v[186:189], v[112:115]
	v_mfma_f32_16x16x32_f16 v[108:111], v[152:155], v[194:197], v[108:111]
	v_mfma_f32_16x16x32_f16 v[104:107], v[170:173], v[194:197], v[104:107]
	v_mfma_f32_16x16x32_f16 v[100:103], v[152:155], v[202:205], v[100:103]
	v_mfma_f32_16x16x32_f16 v[96:99], v[170:173], v[202:205], v[96:99]
	s_barrier
	s_add_i32 s80, 0, 0x1c000
	s_add_i32 s34, vcc_hi, s84
	v_add_u32_e32 v138, s80, v163
	v_lshl_add_u64 v[160:161], v[160:161], 0, s[12:13]
	s_mov_b32 m0, s34
	ds_read_b128 v[206:209], v138
	ds_read_b128 v[210:213], v138 offset:1024
	ds_read_b128 v[214:217], v138 offset:2048
	ds_read_b128 v[218:221], v138 offset:3072
	global_load_lds_dwordx4 v[160:161], off
	v_lshl_add_u64 v[160:161], v[222:223], 0, s[12:13]
	s_add_i32 m0, s34, 0x2000
	s_nop 0
	global_load_lds_dwordx4 v[160:161], off
	s_barrier
; #define PG8_STAGE(bufoff, gbase, voff) do { _Pragma("unroll") for (int _i = 0; _i < 2; ++_i) \
;         __builtin_amdgcn_global_load_lds((const unsigned*)((const char*)(gbase) + (voff)[_i]), (LAS unsigned*)(lds + (bufoff) + ldsw + _i * 8192), 16, 0, 0); } while (0)
; #define PG8_LDA(dst, b, h) do { _Pragma("unroll") for (int m = 0; m < 4; ++m) _Pragma("unroll") for (int k = 0; k < 2; ++k) dst[m][k] = *(const LAS h16x8*)(lds + PG8_SA(b, h) + aoff + m * 2048 + k * 1024); } while (0)
; #define PG8_LDB(dst, b, h) do { _Pragma("unroll") for (int n = 0; n < 2; ++n) _Pragma("unroll") for (int k = 0; k < 2; ++k) dst[n][k] = *(const LAS h16x8*)(lds + PG8_SB(b, h) + boff + n * 2048 + k * 1024); } while (0)
; #define PG8_WAIT_V(n) asm volatile("s_waitcnt vmcnt(" #n ")" ::: "memory")
; #define PG8_WAIT_L(n) asm volatile("s_waitcnt lgkmcnt(" #n ")" ::: "memory")
; #define PG8_BAR __builtin_amdgcn_s_barrier()
; #define PG8_SCHED __builtin_amdgcn_sched_barrier(0)
; template <class Epi>
; __device__ __forceinline__ void gemm_phase(LAS unsigned char* lds, const Gemm g, const StaticOrder& S, const Epi& E) {
;     ...
;             PG8_WAIT_V(6); PG8_BAR; PG8_MMA(1, 1, At, B1); PG8_BAR;
;             PG8_LDB(B0, 1, 0); PG8_SCHED; PG8_LDA(At, 1, 0); PG8_STAGE(PG8_SA(0, 1), a2 + hstep, voffA);
;             PG8_WAIT_L(8); PG8_BAR; PG8_WAIT_L(0); PG8_MMA(0, 0, At, B0); PG8_BAR; PG8_SCHED;
;             PG8_LDB(B1, 1, 1); PG8_STAGE(PG8_SB(1, 0), b3, voffB);
;             PG8_BAR; PG8_WAIT_L(0); PG8_MMA(0, 1, At, B1); PG8_BAR;
;             PG8_LDA(At, 1, 1); PG8_STAGE(PG8_SA(1, 0), a3, voffA);
;             PG8_BAR; PG8_WAIT_L(0); PG8_MMA(1, 0, At, B0); PG8_BAR; PG8_SCHED;
;             PG8_STAGE(PG8_SB(1, 1), b3 + hstep, voffB);
;             PG8_WAIT_V(6); PG8_BAR; PG8_MMA(1, 1, At, B1); PG8_BAR;
;     __device__ __forceinline__ void operator()(const f32x4 (&acc)[2][2][4][2], const pg8::Unit& u, int wr, int wc, int fr, int fq) const {
;         const int row0 = u.pm * 256 + wr * 64 + fr, col0 = u.pn * 256 + wc * 32 + 8 * fq;
; #pragma unroll
;         for (int bj = 0; bj < 2; ++bj) { const int c = col0 + bj * 128;
;             h16* base; size_t ld;
;             if (c < 3200) { base = PC + c; ld = 3200; }
;             else if (c < 4224) { base = ZCD + (c - 3200); ld = 1536; }
;             else if (c < 4736) {
	s_waitcnt lgkmcnt(0)
	s_waitcnt lgkmcnt(0)
	v_mfma_f32_16x16x32_f16 v[60:63], v[206:209], v[174:177], v[60:63]
	v_mfma_f32_16x16x32_f16 v[56:59], v[214:217], v[174:177], v[56:59]
	v_mfma_f32_16x16x32_f16 v[52:55], v[206:209], v[182:185], v[52:55]
	v_mfma_f32_16x16x32_f16 v[48:51], v[214:217], v[182:185], v[48:51]
	v_mfma_f32_16x16x32_f16 v[44:47], v[206:209], v[190:193], v[44:47]
	v_mfma_f32_16x16x32_f16 v[40:43], v[214:217], v[190:193], v[40:43]
	v_mfma_f32_16x16x32_f16 v[36:39], v[206:209], v[198:201], v[36:39]
	v_mfma_f32_16x16x32_f16 v[32:35], v[214:217], v[198:201], v[32:35]
	v_mfma_f32_16x16x32_f16 v[60:63], v[210:213], v[178:181], v[60:63]
	v_mfma_f32_16x16x32_f16 v[56:59], v[218:221], v[178:181], v[56:59]
	v_mfma_f32_16x16x32_f16 v[52:55], v[210:213], v[186:189], v[52:55]
	v_mfma_f32_16x16x32_f16 v[48:51], v[218:221], v[186:189], v[48:51]
	v_mfma_f32_16x16x32_f16 v[44:47], v[210:213], v[194:197], v[44:47]
	v_mfma_f32_16x16x32_f16 v[40:43], v[218:221], v[194:197], v[40:43]
	v_mfma_f32_16x16x32_f16 v[36:39], v[210:213], v[202:205], v[36:39]
	v_mfma_f32_16x16x32_f16 v[32:35], v[218:221], v[202:205], v[32:35]
	s_mov_b32 m0, s92
	v_lshl_add_u64 v[160:161], v[224:225], 0, s[12:13]
	s_barrier
	ds_read_b128 v[174:177], v166 offset:49152
	ds_read_b128 v[178:181], v166 offset:50176
	ds_read_b128 v[182:185], v166 offset:51200
	ds_read_b128 v[186:189], v166 offset:52224
	ds_read_b128 v[190:193], v166 offset:53248
	ds_read_b128 v[194:197], v166 offset:54272
	ds_read_b128 v[198:201], v166 offset:55296
	ds_read_b128 v[202:205], v166 offset:56320
	global_load_lds_dwordx4 v[160:161], off
	v_lshl_add_u64 v[160:161], v[226:227], 0, s[12:13]
	s_mov_b32 m0, s93
	s_nop 0
	global_load_lds_dwordx4 v[160:161], off
	s_barrier
	s_waitcnt lgkmcnt(0)
	s_waitcnt lgkmcnt(0)
	v_mfma_f32_16x16x32_f16 v[92:95], v[148:151], v[174:177], v[92:95]
	v_mfma_f32_16x16x32_f16 v[88:91], v[156:159], v[174:177], v[88:91]
	v_mfma_f32_16x16x32_f16 v[84:87], v[148:151], v[182:185], v[84:87]
	v_mfma_f32_16x16x32_f16 v[80:83], v[156:159], v[182:185], v[80:83]
	v_mfma_f32_16x16x32_f16 v[76:79], v[148:151], v[190:193], v[76:79]
	v_mfma_f32_16x16x32_f16 v[72:75], v[156:159], v[190:193], v[72:75]
	v_mfma_f32_16x16x32_f16 v[68:71], v[148:151], v[198:201], v[68:71]
	v_mfma_f32_16x16x32_f16 v[64:67], v[156:159], v[198:201], v[64:67]
	v_mfma_f32_16x16x32_f16 v[92:95], v[152:155], v[178:181], v[92:95]
	v_mfma_f32_16x16x32_f16 v[88:91], v[170:173], v[178:181], v[88:91]
	v_mfma_f32_16x16x32_f16 v[84:87], v[152:155], v[186:189], v[84:87]
	v_mfma_f32_16x16x32_f16 v[80:83], v[170:173], v[186:189], v[80:83]
	v_mfma_f32_16x16x32_f16 v[76:79], v[152:155], v[194:197], v[76:79]
	v_mfma_f32_16x16x32_f16 v[72:75], v[170:173], v[194:197], v[72:75]
	v_mfma_f32_16x16x32_f16 v[68:71], v[152:155], v[202:205], v[68:71]
	v_mfma_f32_16x16x32_f16 v[64:67], v[170:173], v[202:205], v[64:67]
	s_barrier
	s_add_u32 s34, s78, 0x40080
	s_addc_u32 s35, s79, 0
	s_add_i32 s78, s80, s84
	v_lshl_add_u64 v[148:149], s[34:35], 0, v[132:133]
	s_mov_b32 m0, s78
	s_nop 0
	global_load_lds_dwordx4 v[148:149], off
	v_lshl_add_u64 v[148:149], s[34:35], 0, v[136:137]
	s_add_i32 m0, s78, 0x2000
	s_nop 0
	global_load_lds_dwordx4 v[148:149], off
	s_waitcnt vmcnt(6)
	s_barrier
	v_mfma_f32_16x16x32_f16 v[28:31], v[206:209], v[174:177], v[28:31]
	v_mfma_f32_16x16x32_f16 v[24:27], v[214:217], v[174:177], v[24:27]
	v_mfma_f32_16x16x32_f16 v[20:23], v[206:209], v[182:185], v[20:23]
	v_mfma_f32_16x16x32_f16 v[16:19], v[214:217], v[182:185], v[16:19]
	v_mfma_f32_16x16x32_f16 v[12:15], v[206:209], v[190:193], v[12:15]
	v_mfma_f32_16x16x32_f16 v[8:11], v[214:217], v[190:193], v[8:11]
	v_mfma_f32_16x16x32_f16 v[4:7], v[206:209], v[198:201], v[4:7]
	v_mfma_f32_16x16x32_f16 v[0:3], v[214:217], v[198:201], v[0:3]
	v_mfma_f32_16x16x32_f16 v[28:31], v[210:213], v[178:181], v[28:31]
	v_mfma_f32_16x16x32_f16 v[24:27], v[218:221], v[178:181], v[24:27]
	v_mfma_f32_16x16x32_f16 v[20:23], v[210:213], v[186:189], v[20:23]
	v_mfma_f32_16x16x32_f16 v[16:19], v[218:221], v[186:189], v[16:19]
	v_mfma_f32_16x16x32_f16 v[12:15], v[210:213], v[194:197], v[12:15]
	v_mfma_f32_16x16x32_f16 v[8:11], v[218:221], v[194:197], v[8:11]
	v_mfma_f32_16x16x32_f16 v[4:7], v[210:213], v[202:205], v[4:7]
	v_mfma_f32_16x16x32_f16 v[0:3], v[218:221], v[202:205], v[0:3]
	s_add_i32 s15, s15, 2
	s_add_u32 s76, s76, 0x100
	s_addc_u32 s77, s77, 0
	s_add_u32 vcc_lo, vcc_lo, 0x100
	s_addc_u32 s14, s14, 0
	s_cmp_gt_u32 s15, 13
	s_barrier
	s_cbranch_scc0 .LBB0_485
	s_lshl_b32 s14, s54, 8
	v_or_b32_e32 v154, s14, v164
	v_lshl_add_u32 v148, s56, 8, v162
	v_cmp_lt_i32_e32 vcc, s97, v154
	s_mov_b64 s[56:57], 0
	s_and_saveexec_b64 s[34:35], vcc
	s_xor_b64 s[54:55], exec, s[34:35]
	s_cbranch_execz .LBB0_498
	s_cmpk_gt_u32 s14, 0x107f
	s_cbranch_scc0 .LBB0_491
	s_cmpk_gt_u32 s14, 0x127f
	s_cbranch_scc0 .LBB0_492
	s_mov_b64 s[76:77], 0
	s_cmpk_lt_u32 s14, 0x1480
	s_cbranch_scc0 .LBB0_493
	v_mov_b32_e32 v155, v139
	v_lshl_add_u64 v[150:151], v[154:155], 1, s[8:9]
	v_lshl_add_u64 v[158:159], v[150:151], 0, s[18:19]
	s_mov_b64 s[56:57], -1
	s_branch .LBB0_493

; #define LAS __attribute__((address_space(3)))
; #define PG8_BAR __builtin_amdgcn_s_barrier()
;     __host__ __device__ bool next(int i, Unit& u) const {
;         const long L = (long)i * G + c; if (L >= nwg) return false;
;         int wgid = (int)L; { const int q = nwg / NXCD, r = nwg % NXCD, xcd = wgid % NXCD, off = wgid / NXCD; wgid = (xcd < r ? xcd * (q + 1) : r * (q + 1) + (xcd - r) * q) + off; }
;         const int nig = WGM * nN, gid = wgid / nig, fm = gid * WGM, gsz = (nM - fm) < WGM ? (nM - fm) : WGM;
;         u.pm = fm + ((wgid % nig) % gsz); u.pn = (wgid % nig) / gsz; return true;
;     }
; template <class Epi>
; __device__ __forceinline__ void gemm_phase(LAS unsigned char* lds, const Gemm g, const StaticOrder& S, const Epi& E) {
;     const int tid = threadIdx.x, wid = __builtin_amdgcn_readfirstlane(tid >> 6), lane = tid & 63, wr = wid >> 2, wc = wid & 3, fr = lane & 15, fq = lane >> 4;
;     const int K = g.K, nt = K / BK;
;     unsigned voffA[2], voffB[2];
; #pragma unroll
;     for (int i = 0; i < 2; ++i) { int R, C; stage_rc(tid * 16 + i * 8192, R, C); const int Rb = Epi::PERM ? ((R & ~31) + perm32(R & 31)) : R; voffA[i] = (unsigned)(R * K + C) * 2u; voffB[i] = (unsigned)(Rb * K + C) * 2u; }
;     const size_t kstep = (size_t)(BK * 2);
;     const size_t hstep = (size_t)HALF * K * 2;
;     const size_t tstep = 2 * hstep;
;     const unsigned ldsw = (unsigned)wid * 1024u;
;     const int aoff = lds_byte(wr * 64 + fr, fq * 8), boff = lds_byte(wc * 32 + fr, fq * 8);
;     ...
;     Unit cur, nxt; int ui = 0;
;     if (!S.next(0, cur)) return;
;     f32x4 acc[2][2][4][2];
; #pragma unroll
;     for (int a = 0; a < 2; ++a)
; #pragma unroll
;         for (int b = 0; b < 2; ++b)
; #pragma unroll
;             for (int m = 0; m < 4; ++m)
; #pragma unroll
;                 for (int n = 0; n < 2; ++n) acc[a][b][m][n] = (f32x4){0.f, 0.f, 0.f, 0.f};
;     h16x8 At[4][2], B0[2][2], B1[2][2];
;     const char* cA = (const char*)g.A + (size_t)cur.pm * tstep; const char* cB = (const char*)g.Bt + (size_t)cur.pn * tstep;
;     PG8_STAGE(PG8_SB(0, 0), cB, voffB); PG8_STAGE(PG8_SA(0, 0), cA, voffA); PG8_STAGE(PG8_SB(0, 1), cB + hstep, voffB); PG8_STAGE(PG8_SA(0, 1), cA + hstep, voffA);
;     if (wr == 1) PG8_BAR;
.LBB0_745:
	s_cmp_lt_i32 s72, 12
	s_cselect_b64 s[0:1], -1, 0
	s_and_b64 s[8:9], s[0:1], s[4:5]
	s_andn2_b64 vcc, exec, s[8:9]
	s_cbranch_vccnz .LBB0_766
	s_cmpk_gt_i32 s2, 0xff
	v_readfirstlane_b32 s33, v130
	s_cbranch_scc1 .LBB0_766
	s_add_u32 s36, s70, 0xa800000
	s_addc_u32 s37, s71, 0
	v_lshrrev_b32_e32 v3, 1, v130
	s_add_u32 s38, s70, 0x1c80000
	s_waitcnt vmcnt(0)
	v_and_b32_e32 v10, 24, v3
	v_lshrrev_b32_e32 v3, 5, v130
	s_addc_u32 s39, s71, 0
	v_and_b32_e32 v3, 4, v3
	v_bfe_u32 v4, v130, 2, 2
	s_ashr_i32 s41, s2, 31
	v_lshlrev_b32_e32 v0, 4, v130
	v_and_b32_e32 v1, 32, v130
	v_bfe_u32 v2, v130, 2, 4
	v_or3_b32 v3, v3, v4, v10
	v_lshrrev_b32_e32 v4, 3, v130
	s_movk_i32 s0, 0x70
	s_lshr_b32 s1, s41, 29
	v_bitop3_b32 v8, v0, v1, 48 bitop3:0x6c
	v_and_or_b32 v5, v4, s0, v2
	s_movk_i32 s0, 0x60
	v_add_u32_e32 v0, 0x2000, v0
	s_add_i32 s1, s2, s1
	v_and_or_b32 v4, v4, s0, v3
	v_lshrrev_b32_e32 v0, 7, v0
	s_movk_i32 s0, 0xf0
	s_ashr_i32 s5, s1, 3
	s_and_b32 s1, s1, -8
	v_and_or_b32 v2, v0, s0, v2
	s_movk_i32 s0, 0xe0
	s_lshr_b32 s4, s33, 6
	s_sub_i32 s1, s2, s1
	v_and_or_b32 v0, v0, s0, v3
	s_lshr_b32 s0, s33, 8
	s_lshl_b32 s40, s4, 10
	s_lshl_b32 s7, s1, 5
	s_mul_i32 s6, s1, 33
	s_cmp_lt_i32 s1, 0
	s_cselect_b32 s1, s6, s7
	s_add_i32 s1, s1, s5
	s_ashr_i32 s5, s1, 31
	s_lshr_b32 s5, s5, 27
	s_add_i32 s5, s1, s5
	s_ashr_i32 s6, s5, 5
	s_and_b32 s5, s5, 0xffe0
	s_sub_i32 s5, s1, s5
	s_bfe_i32 s1, s5, 0x80000
	s_bfe_u32 s1, s1, 0x3000c
	s_add_i32 s7, s5, s1
	s_bfe_i32 s1, s7, 0x80000
	s_and_b32 s7, s7, 0xf8
	s_sext_i32_i16 s10, s1
	s_sub_i32 s5, s5, s7
	v_and_b32_e32 v9, 64, v130
	s_lshl_b32 s6, s6, 3
	s_sext_i32_i8 s5, s5
	s_ashr_i32 s7, s10, 3
	v_or_b32_e32 v1, v8, v9
	s_lshr_b32 s1, s10, 3
	s_add_i32 s58, s6, s5
	s_mul_hi_i32 s10, s7, 0xc0000
	s_mul_i32 s7, s7, 0xc0000
	v_lshrrev_b32_e32 v1, 1, v1
	v_mul_u32_u24_e32 v4, 0x600, v4
	s_add_u32 s28, s38, s7
	v_or_b32_e32 v4, v4, v1
	s_addc_u32 s29, s39, s10
	s_add_i32 s42, s40, 0
	v_lshlrev_b32_e32 v132, 1, v4
	v_mul_u32_u24_e32 v0, 0x600, v0
	s_add_i32 m0, s42, 0x10000
	v_mul_u32_u24_e32 v11, 0x600, v5
	v_or_b32_e32 v0, v0, v1
	s_mul_i32 s6, s58, 0xc0000
	global_load_lds_dwordx4 v132, s[28:29]
	s_add_i32 m0, s42, 0x12000
	v_or_b32_e32 v5, v1, v11
	v_mul_u32_u24_e32 v12, 0x600, v2
	v_lshlrev_b32_e32 v136, 1, v0
	s_mul_hi_i32 s5, s58, 0xc0000
	s_add_u32 s26, s36, s6
	v_lshlrev_b32_e32 v128, 1, v5
	v_or_b32_e32 v2, v12, v1
	global_load_lds_dwordx4 v136, s[28:29]
	s_addc_u32 s27, s37, s5
	s_mov_b32 m0, s42
	s_add_i32 s43, s42, 0x2000
	v_lshlrev_b32_e32 v134, 1, v2
	global_load_lds_dwordx4 v128, s[26:27]
	s_mov_b32 m0, s43
	s_add_u32 s6, s28, 0x60000
	global_load_lds_dwordx4 v134, s[26:27]
	s_addc_u32 s7, s29, 0
	s_add_i32 m0, s42, 0x14000
	v_mov_b32_e32 v133, 0
	global_load_lds_dwordx4 v132, s[6:7]
	s_add_i32 m0, s42, 0x16000
	v_mov_b32_e32 v137, v133
	global_load_lds_dwordx4 v136, s[6:7]
	s_add_u32 s6, s26, 0x60000
	s_addc_u32 s7, s27, 0
	s_add_i32 s44, s42, 0x4000
	s_mov_b32 m0, s44
	s_add_i32 s45, s42, 0x6000
	global_load_lds_dwordx4 v128, s[6:7]
	s_mov_b32 m0, s45
	v_mov_b32_e32 v129, v133
	global_load_lds_dwordx4 v134, s[6:7]
	v_mov_b32_e32 v135, v133
	s_mov_b32 s46, 0
	v_lshl_add_u64 v[6:7], s[28:29], 0, v[132:133]
	v_lshl_add_u64 v[4:5], s[28:29], 0, v[136:137]
	v_lshl_add_u64 v[2:3], s[26:27], 0, v[128:129]
	s_cmp_lg_u32 s0, 1
	v_lshl_add_u64 v[0:1], s[26:27], 0, v[134:135]
	s_cbranch_scc1 .LBB0_749
	s_barrier
	s_setprio 1

; #define PG8_STAGE(bufoff, gbase, voff) do { _Pragma("unroll") for (int _i = 0; _i < 2; ++_i) \
;         __builtin_amdgcn_global_load_lds((const unsigned*)((const char*)(gbase) + (voff)[_i]), (LAS unsigned*)(lds + (bufoff) + ldsw + _i * 8192), 16, 0, 0); } while (0)
; #define PG8_LDA(dst, b, h) do { _Pragma("unroll") for (int m = 0; m < 4; ++m) _Pragma("unroll") for (int k = 0; k < 2; ++k) dst[m][k] = *(const LAS h16x8*)(lds + PG8_SA(b, h) + aoff + m * 2048 + k * 1024); } while (0)
; #define PG8_LDB(dst, b, h) do { _Pragma("unroll") for (int n = 0; n < 2; ++n) _Pragma("unroll") for (int k = 0; k < 2; ++k) dst[n][k] = *(const LAS h16x8*)(lds + PG8_SB(b, h) + boff + n * 2048 + k * 1024); } while (0)
; #define PG8_MMA(ai, bj, At, Bt) do { __builtin_amdgcn_s_setprio(1); _Pragma("unroll") for (int m = 0; m < 4; ++m) _Pragma("unroll") for (int n = 0; n < 2; ++n) _Pragma("unroll") for (int k = 0; k < 2; ++k) \
;         acc[ai][bj][m][n] = __builtin_amdgcn_mfma_f32_16x16x32_f16(Bt[n][k], At[m][k], acc[ai][bj][m][n], 0, 0, 0); __builtin_amdgcn_s_setprio(0); } while (0)
; #define PG8_WAIT_L(n) asm volatile("s_waitcnt lgkmcnt(" #n ")" ::: "memory")
; #define PG8_BAR __builtin_amdgcn_s_barrier()
; #define PG8_SCHED __builtin_amdgcn_sched_barrier(0)
; template <class Epi>
; __device__ __forceinline__ void gemm_phase(LAS unsigned char* lds, const Gemm g, const StaticOrder& S, const Epi& E) {
;     ...
;             PG8_LDB(B0, 0, 0); PG8_SCHED; PG8_LDA(At, 0, 0); PG8_STAGE(PG8_SA(1, 1), a1 + hstep, voffA);
;             PG8_WAIT_L(8); PG8_BAR; PG8_WAIT_L(0); PG8_MMA(0, 0, At, B0); PG8_BAR; PG8_SCHED;
;             PG8_LDB(B1, 0, 1); PG8_STAGE(PG8_SB(0, 0), b2, voffB);
;             PG8_BAR; PG8_WAIT_L(0); PG8_MMA(0, 1, At, B1); PG8_BAR;
;             PG8_LDA(At, 0, 1); PG8_STAGE(PG8_SA(0, 0), a2, voffA);
;             PG8_BAR; PG8_WAIT_L(0); PG8_MMA(1, 0, At, B0); PG8_BAR; PG8_SCHED;
;             PG8_STAGE(PG8_SB(0, 1), b2 + hstep, voffB);
.LBB0_761:
	ds_read_b128 v[152:155], v149
	ds_read_b128 v[156:159], v149 offset:1024
	ds_read_b128 v[160:163], v149 offset:2048
	ds_read_b128 v[164:167], v149 offset:3072
	s_add_u32 s28, s26, 0xfffa0080
	s_addc_u32 s29, s27, -1
	s_cmp_eq_u32 s15, 20
	s_cselect_b32 s31, s1, s29
	s_cselect_b32 s30, s0, s28
	s_cselect_b32 s29, s5, s14
	s_cselect_b32 s28, s4, s62
	v_lshl_add_u64 v[200:201], s[26:27], 0, v[138:139]
	s_add_i32 m0, s42, 0xc000
	ds_read_b128 v[168:171], v150
	ds_read_b128 v[172:175], v150 offset:1024
	ds_read_b128 v[176:179], v150 offset:2048
	ds_read_b128 v[180:183], v150 offset:3072
	ds_read_b128 v[184:187], v150 offset:4096
	ds_read_b128 v[188:191], v150 offset:5120
	ds_read_b128 v[192:195], v150 offset:6144
	ds_read_b128 v[196:199], v150 offset:7168
	global_load_lds_dwordx4 v[200:201], off
	v_lshl_add_u64 v[200:201], s[26:27], 0, v[140:141]
	s_add_i32 m0, s42, 0xe000
	s_nop 0
	global_load_lds_dwordx4 v[200:201], off
	s_waitcnt lgkmcnt(8)
	s_barrier
	s_waitcnt lgkmcnt(0)
	s_waitcnt lgkmcnt(0)
	v_mfma_f32_16x16x32_f16 v[124:127], v[152:155], v[168:171], v[124:127]
	v_mfma_f32_16x16x32_f16 v[120:123], v[160:163], v[168:171], v[120:123]
	v_mfma_f32_16x16x32_f16 v[116:119], v[152:155], v[176:179], v[116:119]
	v_mfma_f32_16x16x32_f16 v[112:115], v[160:163], v[176:179], v[112:115]
	v_mfma_f32_16x16x32_f16 v[100:103], v[152:155], v[184:187], v[100:103]
	v_mfma_f32_16x16x32_f16 v[96:99], v[160:163], v[184:187], v[96:99]
	v_mfma_f32_16x16x32_f16 v[84:87], v[152:155], v[192:195], v[84:87]
	v_mfma_f32_16x16x32_f16 v[80:83], v[160:163], v[192:195], v[80:83]
	v_mfma_f32_16x16x32_f16 v[124:127], v[156:159], v[172:175], v[124:127]
	v_mfma_f32_16x16x32_f16 v[120:123], v[164:167], v[172:175], v[120:123]
	v_mfma_f32_16x16x32_f16 v[116:119], v[156:159], v[180:183], v[116:119]
	v_mfma_f32_16x16x32_f16 v[112:115], v[164:167], v[180:183], v[112:115]
	v_mfma_f32_16x16x32_f16 v[100:103], v[156:159], v[188:191], v[100:103]
	v_mfma_f32_16x16x32_f16 v[96:99], v[164:167], v[188:191], v[96:99]
	v_mfma_f32_16x16x32_f16 v[84:87], v[156:159], v[196:199], v[84:87]
	v_mfma_f32_16x16x32_f16 v[80:83], v[164:167], v[196:199], v[80:83]
	s_barrier
	s_add_i32 s34, s53, s40
	v_lshl_add_u64 v[216:217], s[28:29], 0, v[132:133]
	s_mov_b32 m0, s34
	ds_read_b128 v[200:203], v151
	ds_read_b128 v[204:207], v151 offset:1024
	ds_read_b128 v[208:211], v151 offset:2048
	ds_read_b128 v[212:215], v151 offset:3072
	global_load_lds_dwordx4 v[216:217], off
	v_lshl_add_u64 v[218:219], s[28:29], 0, v[136:137]
	s_add_i32 m0, s34, 0x2000
	s_nop 0
	global_load_lds_dwordx4 v[218:219], off
	s_barrier
	s_waitcnt lgkmcnt(0)
	s_waitcnt lgkmcnt(0)
	v_mfma_f32_16x16x32_f16 v[108:111], v[200:203], v[168:171], v[108:111]
	v_mfma_f32_16x16x32_f16 v[104:107], v[208:211], v[168:171], v[104:107]
	v_mfma_f32_16x16x32_f16 v[92:95], v[200:203], v[176:179], v[92:95]
	v_mfma_f32_16x16x32_f16 v[88:91], v[208:211], v[176:179], v[88:91]
	v_mfma_f32_16x16x32_f16 v[76:79], v[200:203], v[184:187], v[76:79]
	v_mfma_f32_16x16x32_f16 v[72:75], v[208:211], v[184:187], v[72:75]
	v_mfma_f32_16x16x32_f16 v[68:71], v[200:203], v[192:195], v[68:71]
	v_mfma_f32_16x16x32_f16 v[64:67], v[208:211], v[192:195], v[64:67]
	v_mfma_f32_16x16x32_f16 v[108:111], v[204:207], v[172:175], v[108:111]
	v_mfma_f32_16x16x32_f16 v[104:107], v[212:215], v[172:175], v[104:107]
	v_mfma_f32_16x16x32_f16 v[92:95], v[204:207], v[180:183], v[92:95]
	v_mfma_f32_16x16x32_f16 v[88:91], v[212:215], v[180:183], v[88:91]
	v_mfma_f32_16x16x32_f16 v[76:79], v[204:207], v[188:191], v[76:79]
	v_mfma_f32_16x16x32_f16 v[72:75], v[212:215], v[188:191], v[72:75]
	v_mfma_f32_16x16x32_f16 v[68:71], v[204:207], v[196:199], v[68:71]
	v_mfma_f32_16x16x32_f16 v[64:67], v[212:215], v[196:199], v[64:67]
	s_mov_b32 m0, s42
	v_lshl_add_u64 v[220:221], s[30:31], 0, v[128:129]
	s_barrier
	ds_read_b128 v[168:171], v150 offset:16384
	ds_read_b128 v[172:175], v150 offset:17408
	ds_read_b128 v[176:179], v150 offset:18432
	ds_read_b128 v[180:183], v150 offset:19456
	ds_read_b128 v[184:187], v150 offset:20480
	ds_read_b128 v[188:191], v150 offset:21504
	ds_read_b128 v[192:195], v150 offset:22528
	ds_read_b128 v[196:199], v150 offset:23552
	global_load_lds_dwordx4 v[220:221], off
	v_lshl_add_u64 v[222:223], s[30:31], 0, v[134:135]
	s_mov_b32 m0, s43
	s_nop 0
	global_load_lds_dwordx4 v[222:223], off
	s_barrier
	s_waitcnt lgkmcnt(0)
	s_waitcnt lgkmcnt(0)
	v_mfma_f32_16x16x32_f16 v[60:63], v[152:155], v[168:171], v[60:63]
	v_mfma_f32_16x16x32_f16 v[56:59], v[160:163], v[168:171], v[56:59]
	v_mfma_f32_16x16x32_f16 v[52:55], v[152:155], v[176:179], v[52:55]
	v_mfma_f32_16x16x32_f16 v[48:51], v[160:163], v[176:179], v[48:51]
	v_mfma_f32_16x16x32_f16 v[36:39], v[152:155], v[184:187], v[36:39]
	v_mfma_f32_16x16x32_f16 v[32:35], v[160:163], v[184:187], v[32:35]
	v_mfma_f32_16x16x32_f16 v[20:23], v[152:155], v[192:195], v[20:23]
	v_mfma_f32_16x16x32_f16 v[16:19], v[160:163], v[192:195], v[16:19]
	v_mfma_f32_16x16x32_f16 v[60:63], v[156:159], v[172:175], v[60:63]
	v_mfma_f32_16x16x32_f16 v[56:59], v[164:167], v[172:175], v[56:59]
	v_mfma_f32_16x16x32_f16 v[52:55], v[156:159], v[180:183], v[52:55]
	v_mfma_f32_16x16x32_f16 v[48:51], v[164:167], v[180:183], v[48:51]
	v_mfma_f32_16x16x32_f16 v[36:39], v[156:159], v[188:191], v[36:39]
	v_mfma_f32_16x16x32_f16 v[32:35], v[164:167], v[188:191], v[32:35]
	v_mfma_f32_16x16x32_f16 v[20:23], v[156:159], v[196:199], v[20:23]
	v_mfma_f32_16x16x32_f16 v[16:19], v[164:167], v[196:199], v[16:19]
	s_barrier
; #define PG8_STAGE(bufoff, gbase, voff) do { _Pragma("unroll") for (int _i = 0; _i < 2; ++_i) \
;         __builtin_amdgcn_global_load_lds((const unsigned*)((const char*)(gbase) + (voff)[_i]), (LAS unsigned*)(lds + (bufoff) + ldsw + _i * 8192), 16, 0, 0); } while (0)
; #define PG8_LDA(dst, b, h) do { _Pragma("unroll") for (int m = 0; m < 4; ++m) _Pragma("unroll") for (int k = 0; k < 2; ++k) dst[m][k] = *(const LAS h16x8*)(lds + PG8_SA(b, h) + aoff + m * 2048 + k * 1024); } while (0)
; #define PG8_LDB(dst, b, h) do { _Pragma("unroll") for (int n = 0; n < 2; ++n) _Pragma("unroll") for (int k = 0; k < 2; ++k) dst[n][k] = *(const LAS h16x8*)(lds + PG8_SB(b, h) + boff + n * 2048 + k * 1024); } while (0)
; #define PG8_MMA(ai, bj, At, Bt) do { __builtin_amdgcn_s_setprio(1); _Pragma("unroll") for (int m = 0; m < 4; ++m) _Pragma("unroll") for (int n = 0; n < 2; ++n) _Pragma("unroll") for (int k = 0; k < 2; ++k) \
;         acc[ai][bj][m][n] = __builtin_amdgcn_mfma_f32_16x16x32_f16(Bt[n][k], At[m][k], acc[ai][bj][m][n], 0, 0, 0); __builtin_amdgcn_s_setprio(0); } while (0)
; #define PG8_WAIT_V(n) asm volatile("s_waitcnt vmcnt(" #n ")" ::: "memory")
; #define PG8_WAIT_L(n) asm volatile("s_waitcnt lgkmcnt(" #n ")" ::: "memory")
; #define PG8_BAR __builtin_amdgcn_s_barrier()
; #define PG8_SCHED __builtin_amdgcn_sched_barrier(0)
; template <class Epi>
; __device__ __forceinline__ void gemm_phase(LAS unsigned char* lds, const Gemm g, const StaticOrder& S, const Epi& E) {
;     ...
;             PG8_STAGE(PG8_SB(0, 1), b2 + hstep, voffB);
;             PG8_WAIT_V(6); PG8_BAR; PG8_MMA(1, 1, At, B1); PG8_BAR;
;             PG8_LDB(B0, 1, 0); PG8_SCHED; PG8_LDA(At, 1, 0); PG8_STAGE(PG8_SA(0, 1), a2 + hstep, voffA);
;             PG8_WAIT_L(8); PG8_BAR; PG8_WAIT_L(0); PG8_MMA(0, 0, At, B0); PG8_BAR; PG8_SCHED;
;             PG8_LDB(B1, 1, 1); PG8_STAGE(PG8_SB(1, 0), b3, voffB);
;             PG8_BAR; PG8_WAIT_L(0); PG8_MMA(0, 1, At, B1); PG8_BAR;
;             PG8_LDA(At, 1, 1); PG8_STAGE(PG8_SA(1, 0), a3, voffA);
;             PG8_BAR; PG8_WAIT_L(0); PG8_MMA(1, 0, At, B0); PG8_BAR; PG8_SCHED;
	s_add_u32 s34, s28, 0x60000
	s_addc_u32 s35, s29, 0
	s_add_i32 s63, s54, s40
	v_lshl_add_u64 v[152:153], s[34:35], 0, v[132:133]
	s_mov_b32 m0, s63
	s_nop 0
	global_load_lds_dwordx4 v[152:153], off
	v_lshl_add_u64 v[152:153], s[34:35], 0, v[136:137]
	s_add_i32 m0, s63, 0x2000
	s_nop 0
	global_load_lds_dwordx4 v[152:153], off
	s_waitcnt vmcnt(6)
	s_barrier
	v_mfma_f32_16x16x32_f16 v[44:47], v[200:203], v[168:171], v[44:47]
	v_mfma_f32_16x16x32_f16 v[40:43], v[208:211], v[168:171], v[40:43]
	v_mfma_f32_16x16x32_f16 v[28:31], v[200:203], v[176:179], v[28:31]
	v_mfma_f32_16x16x32_f16 v[24:27], v[208:211], v[176:179], v[24:27]
	v_mfma_f32_16x16x32_f16 v[12:15], v[200:203], v[184:187], v[12:15]
	v_mfma_f32_16x16x32_f16 v[8:11], v[208:211], v[184:187], v[8:11]
	v_mfma_f32_16x16x32_f16 v[4:7], v[200:203], v[192:195], v[4:7]
	v_mfma_f32_16x16x32_f16 v[0:3], v[208:211], v[192:195], v[0:3]
	v_mfma_f32_16x16x32_f16 v[44:47], v[204:207], v[172:175], v[44:47]
	v_mfma_f32_16x16x32_f16 v[40:43], v[212:215], v[172:175], v[40:43]
	v_mfma_f32_16x16x32_f16 v[28:31], v[204:207], v[180:183], v[28:31]
	v_mfma_f32_16x16x32_f16 v[24:27], v[212:215], v[180:183], v[24:27]
	v_mfma_f32_16x16x32_f16 v[12:15], v[204:207], v[188:191], v[12:15]
	v_mfma_f32_16x16x32_f16 v[8:11], v[212:215], v[188:191], v[8:11]
	v_mfma_f32_16x16x32_f16 v[4:7], v[204:207], v[196:199], v[4:7]
	v_mfma_f32_16x16x32_f16 v[0:3], v[212:215], v[196:199], v[0:3]
	s_add_i32 s34, 0, 0x18000
	v_add_u32_e32 v164, s34, v147
	s_barrier
	ds_read_b128 v[152:155], v164
	ds_read_b128 v[156:159], v164 offset:1024
	ds_read_b128 v[160:163], v164 offset:2048
	ds_read_b128 v[164:167], v164 offset:3072
	s_add_u32 s30, s30, 0x60000
	s_addc_u32 s31, s31, 0
	s_mov_b32 m0, s44
	v_lshl_add_u64 v[200:201], s[30:31], 0, v[128:129]
	ds_read_b128 v[168:171], v150 offset:32768
	ds_read_b128 v[172:175], v150 offset:33792
	ds_read_b128 v[176:179], v150 offset:34816
	ds_read_b128 v[180:183], v150 offset:35840
	ds_read_b128 v[184:187], v150 offset:36864
	ds_read_b128 v[188:191], v150 offset:37888
	ds_read_b128 v[192:195], v150 offset:38912
	ds_read_b128 v[196:199], v150 offset:39936
	global_load_lds_dwordx4 v[200:201], off
	v_lshl_add_u64 v[200:201], s[30:31], 0, v[134:135]
	s_mov_b32 m0, s45
	s_nop 0
	global_load_lds_dwordx4 v[200:201], off
	s_waitcnt lgkmcnt(8)
	s_barrier
	s_waitcnt lgkmcnt(0)
	s_waitcnt lgkmcnt(0)
	v_mfma_f32_16x16x32_f16 v[124:127], v[152:155], v[168:171], v[124:127]
	v_mfma_f32_16x16x32_f16 v[120:123], v[160:163], v[168:171], v[120:123]
	v_mfma_f32_16x16x32_f16 v[116:119], v[152:155], v[176:179], v[116:119]
	v_mfma_f32_16x16x32_f16 v[112:115], v[160:163], v[176:179], v[112:115]
	v_mfma_f32_16x16x32_f16 v[100:103], v[152:155], v[184:187], v[100:103]
	v_mfma_f32_16x16x32_f16 v[96:99], v[160:163], v[184:187], v[96:99]
	v_mfma_f32_16x16x32_f16 v[84:87], v[152:155], v[192:195], v[84:87]
	v_mfma_f32_16x16x32_f16 v[80:83], v[160:163], v[192:195], v[80:83]
	v_mfma_f32_16x16x32_f16 v[124:127], v[156:159], v[172:175], v[124:127]
	v_mfma_f32_16x16x32_f16 v[120:123], v[164:167], v[172:175], v[120:123]
	v_mfma_f32_16x16x32_f16 v[116:119], v[156:159], v[180:183], v[116:119]
	v_mfma_f32_16x16x32_f16 v[112:115], v[164:167], v[180:183], v[112:115]
	v_mfma_f32_16x16x32_f16 v[100:103], v[156:159], v[188:191], v[100:103]
	v_mfma_f32_16x16x32_f16 v[96:99], v[164:167], v[188:191], v[96:99]
	v_mfma_f32_16x16x32_f16 v[84:87], v[156:159], v[196:199], v[84:87]
	v_mfma_f32_16x16x32_f16 v[80:83], v[164:167], v[196:199], v[80:83]
	s_barrier
	s_add_i32 s30, 0, 0x1c000
	s_add_i32 s31, s34, s40
	v_add_u32_e32 v212, s30, v147
	v_lshl_add_u64 v[216:217], v[216:217], 0, s[12:13]
	s_mov_b32 m0, s31
	ds_read_b128 v[200:203], v212
	ds_read_b128 v[204:207], v212 offset:1024
	ds_read_b128 v[208:211], v212 offset:2048
	ds_read_b128 v[212:215], v212 offset:3072
	global_load_lds_dwordx4 v[216:217], off
	v_lshl_add_u64 v[216:217], v[218:219], 0, s[12:13]
	s_add_i32 m0, s31, 0x2000
	s_nop 0
	global_load_lds_dwordx4 v[216:217], off
	s_barrier
	s_waitcnt lgkmcnt(0)
	s_waitcnt lgkmcnt(0)
	v_mfma_f32_16x16x32_f16 v[108:111], v[200:203], v[168:171], v[108:111]
	v_mfma_f32_16x16x32_f16 v[104:107], v[208:211], v[168:171], v[104:107]
	v_mfma_f32_16x16x32_f16 v[92:95], v[200:203], v[176:179], v[92:95]
	v_mfma_f32_16x16x32_f16 v[88:91], v[208:211], v[176:179], v[88:91]
	v_mfma_f32_16x16x32_f16 v[76:79], v[200:203], v[184:187], v[76:79]
	v_mfma_f32_16x16x32_f16 v[72:75], v[208:211], v[184:187], v[72:75]
	v_mfma_f32_16x16x32_f16 v[68:71], v[200:203], v[192:195], v[68:71]
	v_mfma_f32_16x16x32_f16 v[64:67], v[208:211], v[192:195], v[64:67]
	v_mfma_f32_16x16x32_f16 v[108:111], v[204:207], v[172:175], v[108:111]
	v_mfma_f32_16x16x32_f16 v[104:107], v[212:215], v[172:175], v[104:107]
	v_mfma_f32_16x16x32_f16 v[92:95], v[204:207], v[180:183], v[92:95]
	v_mfma_f32_16x16x32_f16 v[88:91], v[212:215], v[180:183], v[88:91]
	v_mfma_f32_16x16x32_f16 v[76:79], v[204:207], v[188:191], v[76:79]
	v_mfma_f32_16x16x32_f16 v[72:75], v[212:215], v[188:191], v[72:75]
	v_mfma_f32_16x16x32_f16 v[68:71], v[204:207], v[196:199], v[68:71]
	v_mfma_f32_16x16x32_f16 v[64:67], v[212:215], v[196:199], v[64:67]
	s_mov_b32 m0, s48
	v_lshl_add_u64 v[216:217], v[220:221], 0, s[12:13]
	s_barrier
	ds_read_b128 v[168:171], v150 offset:49152
	ds_read_b128 v[172:175], v150 offset:50176
	ds_read_b128 v[176:179], v150 offset:51200
	ds_read_b128 v[180:183], v150 offset:52224
	ds_read_b128 v[184:187], v150 offset:53248
	ds_read_b128 v[188:191], v150 offset:54272
	ds_read_b128 v[192:195], v150 offset:55296
	ds_read_b128 v[196:199], v150 offset:56320
	global_load_lds_dwordx4 v[216:217], off
	v_lshl_add_u64 v[216:217], v[222:223], 0, s[12:13]
	s_mov_b32 m0, s49
	s_nop 0
	global_load_lds_dwordx4 v[216:217], off
	s_barrier
; #define PG8_STAGE(bufoff, gbase, voff) do { _Pragma("unroll") for (int _i = 0; _i < 2; ++_i) \
;         __builtin_amdgcn_global_load_lds((const unsigned*)((const char*)(gbase) + (voff)[_i]), (LAS unsigned*)(lds + (bufoff) + ldsw + _i * 8192), 16, 0, 0); } while (0)
; #define PG8_MMA(ai, bj, At, Bt) do { __builtin_amdgcn_s_setprio(1); _Pragma("unroll") for (int m = 0; m < 4; ++m) _Pragma("unroll") for (int n = 0; n < 2; ++n) _Pragma("unroll") for (int k = 0; k < 2; ++k) \
;         acc[ai][bj][m][n] = __builtin_amdgcn_mfma_f32_16x16x32_f16(Bt[n][k], At[m][k], acc[ai][bj][m][n], 0, 0, 0); __builtin_amdgcn_s_setprio(0); } while (0)
; #define PG8_WAIT_V(n) asm volatile("s_waitcnt vmcnt(" #n ")" ::: "memory")
; #define PG8_WAIT_L(n) asm volatile("s_waitcnt lgkmcnt(" #n ")" ::: "memory")
; #define PG8_BAR __builtin_amdgcn_s_barrier()
; #define PG8_SCHED __builtin_amdgcn_sched_barrier(0)
; template <class Epi>
; __device__ __forceinline__ void gemm_phase(LAS unsigned char* lds, const Gemm g, const StaticOrder& S, const Epi& E) {
;     ...
;             PG8_BAR; PG8_WAIT_L(0); PG8_MMA(1, 0, At, B0); PG8_BAR; PG8_SCHED;
;             PG8_STAGE(PG8_SB(1, 1), b3 + hstep, voffB);
;             PG8_WAIT_V(6); PG8_BAR; PG8_MMA(1, 1, At, B1); PG8_BAR;
	s_waitcnt lgkmcnt(0)
	s_waitcnt lgkmcnt(0)
	v_mfma_f32_16x16x32_f16 v[60:63], v[152:155], v[168:171], v[60:63]
	v_mfma_f32_16x16x32_f16 v[56:59], v[160:163], v[168:171], v[56:59]
	v_mfma_f32_16x16x32_f16 v[52:55], v[152:155], v[176:179], v[52:55]
	v_mfma_f32_16x16x32_f16 v[48:51], v[160:163], v[176:179], v[48:51]
	v_mfma_f32_16x16x32_f16 v[36:39], v[152:155], v[184:187], v[36:39]
	v_mfma_f32_16x16x32_f16 v[32:35], v[160:163], v[184:187], v[32:35]
	v_mfma_f32_16x16x32_f16 v[20:23], v[152:155], v[192:195], v[20:23]
	v_mfma_f32_16x16x32_f16 v[16:19], v[160:163], v[192:195], v[16:19]
	v_mfma_f32_16x16x32_f16 v[60:63], v[156:159], v[172:175], v[60:63]
	v_mfma_f32_16x16x32_f16 v[56:59], v[164:167], v[172:175], v[56:59]
	v_mfma_f32_16x16x32_f16 v[52:55], v[156:159], v[180:183], v[52:55]
	v_mfma_f32_16x16x32_f16 v[48:51], v[164:167], v[180:183], v[48:51]
	v_mfma_f32_16x16x32_f16 v[36:39], v[156:159], v[188:191], v[36:39]
	v_mfma_f32_16x16x32_f16 v[32:35], v[164:167], v[188:191], v[32:35]
	v_mfma_f32_16x16x32_f16 v[20:23], v[156:159], v[196:199], v[20:23]
	v_mfma_f32_16x16x32_f16 v[16:19], v[164:167], v[196:199], v[16:19]
	s_barrier
	s_add_u32 s28, s28, 0x60080
	s_addc_u32 s29, s29, 0
	s_add_i32 s30, s30, s40
	v_lshl_add_u64 v[152:153], s[28:29], 0, v[132:133]
	s_mov_b32 m0, s30
	s_nop 0
	global_load_lds_dwordx4 v[152:153], off
	v_lshl_add_u64 v[152:153], s[28:29], 0, v[136:137]
	s_add_i32 m0, s30, 0x2000
	s_nop 0
	global_load_lds_dwordx4 v[152:153], off
	s_waitcnt vmcnt(6)
	s_barrier
	v_mfma_f32_16x16x32_f16 v[44:47], v[200:203], v[168:171], v[44:47]
	v_mfma_f32_16x16x32_f16 v[40:43], v[208:211], v[168:171], v[40:43]
	v_mfma_f32_16x16x32_f16 v[28:31], v[200:203], v[176:179], v[28:31]
	v_mfma_f32_16x16x32_f16 v[24:27], v[208:211], v[176:179], v[24:27]
	v_mfma_f32_16x16x32_f16 v[12:15], v[200:203], v[184:187], v[12:15]
	v_mfma_f32_16x16x32_f16 v[8:11], v[208:211], v[184:187], v[8:11]
	v_mfma_f32_16x16x32_f16 v[4:7], v[200:203], v[192:195], v[4:7]
	v_mfma_f32_16x16x32_f16 v[0:3], v[208:211], v[192:195], v[0:3]
	v_mfma_f32_16x16x32_f16 v[44:47], v[204:207], v[172:175], v[44:47]
	v_mfma_f32_16x16x32_f16 v[40:43], v[212:215], v[172:175], v[40:43]
	v_mfma_f32_16x16x32_f16 v[28:31], v[204:207], v[180:183], v[28:31]
	v_mfma_f32_16x16x32_f16 v[24:27], v[212:215], v[180:183], v[24:27]
	v_mfma_f32_16x16x32_f16 v[12:15], v[204:207], v[188:191], v[12:15]
	v_mfma_f32_16x16x32_f16 v[8:11], v[212:215], v[188:191], v[8:11]
	v_mfma_f32_16x16x32_f16 v[4:7], v[204:207], v[196:199], v[4:7]
	v_mfma_f32_16x16x32_f16 v[0:3], v[212:215], v[196:199], v[0:3]
	s_add_i32 s15, s15, 2
	s_add_u32 s26, s26, 0x100
	s_addc_u32 s27, s27, 0
	s_add_u32 s62, s62, 0x100
	s_addc_u32 s14, s14, 0
	s_cmp_gt_u32 s15, 21
	s_barrier
	s_cbranch_scc0 .LBB0_761
; #define PG8_WAIT_V(n) asm volatile("s_waitcnt vmcnt(" #n ")" ::: "memory")
; #define PG8_BAR __builtin_amdgcn_s_barrier()
; template <class Epi>
; __device__ __forceinline__ void gemm_phase(LAS unsigned char* lds, const Gemm g, const StaticOrder& S, const Epi& E) {
;     ...
;         cur = nxt; cA = nA; cB = nB; ++ui;
;     }
;     PG8_WAIT_V(0);
;     if (wr == 0) PG8_BAR;
;     PG8_BAR;
;     __device__ __forceinline__ void operator()(const f32x4 (&acc)[2][2][4][2], const pg8::Unit& u, int wr, int wc, int fr, int fq) const {
;         const int row0 = u.pm * 256 + wr * 64 + fr, col0 = u.pn * 256 + wc * 32 + 8 * fq;
; #pragma unroll
;         for (int ai = 0; ai < 2; ++ai)
; #pragma unroll
;             for (int m = 0; m < 4; ++m) { const size_t r = (size_t)(row0 + ai * 128 + m * 16);
; #pragma unroll
;                 for (int bj = 0; bj < 2; ++bj) { const f32x4 v0 = acc[ai][bj][m][0], v1 = acc[ai][bj][m][1]; h16x8 o;
; #pragma unroll
;                     for (int e = 0; e < 4; ++e) { o[e] = (h16)v0[e]; o[4 + e] = (h16)v1[e]; }
;                     *(h16x8*)(O2 + r * 1024 + col0 + bj * 128) = o; } }
;     }
	v_lshl_add_u32 v152, s58, 8, v146
	v_lshl_or_b32 v154, s61, 8, v148
	v_ashrrev_i32_e32 v153, 31, v152
	v_ashrrev_i32_e32 v155, 31, v154
	v_lshlrev_b64 v[156:157], 11, v[152:153]
	v_cvt_pk_f16_f32 v123, v122, v123
	v_cvt_pk_f16_f32 v122, v120, v121
	v_cvt_pk_f16_f32 v121, v126, v127
	v_cvt_pk_f16_f32 v120, v124, v125
	v_lshl_add_u64 v[124:125], s[10:11], 0, v[156:157]
	v_lshlrev_b64 v[126:127], 1, v[154:155]
	v_lshl_add_u64 v[124:125], v[124:125], 0, v[126:127]
	v_cvt_pk_f16_f32 v107, v106, v107
	v_cvt_pk_f16_f32 v106, v104, v105
	v_cvt_pk_f16_f32 v105, v110, v111
	v_cvt_pk_f16_f32 v104, v108, v109
	global_store_dwordx4 v[124:125], v[104:107], off offset:256
	v_cvt_pk_f16_f32 v91, v90, v91
	v_cvt_pk_f16_f32 v90, v88, v89
	v_or_b32_e32 v104, 16, v152
	v_ashrrev_i32_e32 v105, 31, v104
	v_lshlrev_b64 v[108:109], 11, v[104:105]
	v_lshl_add_u64 v[108:109], s[10:11], 0, v[108:109]
	v_lshl_add_u64 v[108:109], v[108:109], 0, v[126:127]
	v_cvt_pk_f16_f32 v89, v94, v95
	v_cvt_pk_f16_f32 v88, v92, v93
	global_store_dwordx4 v[108:109], v[88:91], off offset:256
	v_cvt_pk_f16_f32 v59, v58, v59
	v_cvt_pk_f16_f32 v58, v56, v57
	v_or_b32_e32 v88, 32, v152
	v_ashrrev_i32_e32 v89, 31, v88
	v_cvt_pk_f16_f32 v57, v62, v63
	v_add_co_u32_e32 v62, vcc, s55, v124
	v_lshlrev_b64 v[92:93], 11, v[88:89]
	s_nop 0
	v_addc_co_u32_e32 v63, vcc, 0, v125, vcc
	v_lshl_add_u64 v[92:93], s[10:11], 0, v[92:93]
	v_cvt_pk_f16_f32 v43, v42, v43
	v_cvt_pk_f16_f32 v42, v40, v41
	v_cvt_pk_f16_f32 v41, v46, v47
	v_add_co_u32_e32 v46, vcc, s56, v124
	v_lshl_add_u64 v[92:93], v[92:93], 0, v[126:127]
	v_cvt_pk_f16_f32 v75, v74, v75
	v_cvt_pk_f16_f32 v74, v72, v73
	v_cvt_pk_f16_f32 v73, v78, v79
	v_cvt_pk_f16_f32 v72, v76, v77
	v_addc_co_u32_e32 v47, vcc, 0, v125, vcc
	global_store_dwordx4 v[92:93], v[72:75], off offset:256
	v_cvt_pk_f16_f32 v27, v26, v27
	v_cvt_pk_f16_f32 v26, v24, v25
	v_or_b32_e32 v72, 48, v152
	v_cvt_pk_f16_f32 v25, v30, v31
	v_add_co_u32_e32 v30, vcc, s57, v124
	v_ashrrev_i32_e32 v73, 31, v72
	s_nop 0
	v_addc_co_u32_e32 v31, vcc, 0, v125, vcc
	v_lshlrev_b64 v[76:77], 11, v[72:73]
	v_cvt_pk_f16_f32 v11, v10, v11
	v_cvt_pk_f16_f32 v10, v8, v9
	v_cvt_pk_f16_f32 v9, v14, v15
	v_add_co_u32_e32 v14, vcc, 0x58000, v124
	v_lshl_add_u64 v[76:77], s[10:11], 0, v[76:77]
	v_cvt_pk_f16_f32 v56, v60, v61
	v_lshl_add_u64 v[60:61], v[124:125], 0, s[18:19]
	v_cvt_pk_f16_f32 v40, v44, v45
	v_lshl_add_u64 v[44:45], v[124:125], 0, s[20:21]
	v_cvt_pk_f16_f32 v24, v28, v29
	v_lshl_add_u64 v[28:29], v[124:125], 0, s[22:23]
	v_cvt_pk_f16_f32 v8, v12, v13
	v_addc_co_u32_e32 v15, vcc, 0, v125, vcc
	v_cvt_pk_f16_f32 v107, v114, v115
	v_cvt_pk_f16_f32 v106, v112, v113
	v_cvt_pk_f16_f32 v105, v118, v119
	v_cvt_pk_f16_f32 v104, v116, v117
	v_cvt_pk_f16_f32 v91, v98, v99
	v_cvt_pk_f16_f32 v90, v96, v97
	v_cvt_pk_f16_f32 v89, v102, v103
	v_cvt_pk_f16_f32 v88, v100, v101
	v_cvt_pk_f16_f32 v75, v82, v83
	v_cvt_pk_f16_f32 v74, v80, v81
	v_cvt_pk_f16_f32 v73, v86, v87
	v_cvt_pk_f16_f32 v72, v84, v85
	v_lshl_add_u64 v[76:77], v[76:77], 0, v[126:127]
	v_cvt_pk_f16_f32 v67, v66, v67
	v_cvt_pk_f16_f32 v66, v64, v65
	v_cvt_pk_f16_f32 v65, v70, v71
	v_cvt_pk_f16_f32 v64, v68, v69
	global_store_dwordx4 v[60:61], v[40:43], off offset:256
	global_store_dwordx4 v[44:45], v[24:27], off offset:256
	global_store_dwordx4 v[28:29], v[8:11], off offset:256
	v_cvt_pk_f16_f32 v43, v50, v51
	v_cvt_pk_f16_f32 v42, v48, v49
	v_cvt_pk_f16_f32 v41, v54, v55
	v_cvt_pk_f16_f32 v40, v52, v53
	v_cvt_pk_f16_f32 v27, v34, v35
	v_cvt_pk_f16_f32 v26, v32, v33
	v_cvt_pk_f16_f32 v25, v38, v39
	v_cvt_pk_f16_f32 v24, v36, v37
	v_cvt_pk_f16_f32 v11, v18, v19
	v_cvt_pk_f16_f32 v10, v16, v17
	v_cvt_pk_f16_f32 v9, v22, v23
	v_cvt_pk_f16_f32 v8, v20, v21
	v_lshl_add_u64 v[12:13], v[124:125], 0, s[24:25]
	v_cvt_pk_f16_f32 v3, v2, v3
	v_cvt_pk_f16_f32 v2, v0, v1
	v_cvt_pk_f16_f32 v1, v6, v7
	v_cvt_pk_f16_f32 v0, v4, v5
	s_and_b64 vcc, exec, s[6:7]
	s_mov_b32 s61, s59
	s_mov_b32 s58, s60
	s_mov_b64 s[28:29], s[4:5]
	s_mov_b64 s[26:27], s[0:1]
	global_store_dwordx4 v[124:125], v[120:123], off
	global_store_dwordx4 v[108:109], v[104:107], off
	global_store_dwordx4 v[92:93], v[88:91], off
	global_store_dwordx4 v[76:77], v[72:75], off
	global_store_dwordx4 v[76:77], v[64:67], off offset:256
	global_store_dwordx4 v[62:63], v[56:59], off
	global_store_dwordx4 v[46:47], v[40:43], off
	global_store_dwordx4 v[30:31], v[24:27], off
	global_store_dwordx4 v[14:15], v[8:11], off
	global_store_dwordx4 v[12:13], v[0:3], off offset:256
	s_cbranch_vccz .LBB0_750
	s_waitcnt vmcnt(0)
	s_cmpk_gt_u32 s33, 0xff
	s_cbranch_scc1 .LBB0_765
	s_barrier
